# v19 + attention row-max cross-half exchange via v_permlane32_swap instead of ds_bpermute (no LDS round trip on the softmax critical path)
# speedup vs baseline: 1.0032x; 1.0032x over previous
.LBB0_159:
	ds_read_b128 v[38:41], v134 offset:6656
	ds_read_b128 v[42:45], v134
	ds_read_b128 v[138:141], v134 offset:32
	ds_read_b128 v[142:145], v134 offset:6688
	s_cmp_eq_u32 s25, -1
	s_cselect_b64 s[18:19], -1, 0
	s_waitcnt lgkmcnt(2)
	v_mfma_f32_32x32x16_bf16 v[54:69], v[42:45], v[70:73], 0
	v_cndmask_b32_e64 v146, -v137, v195, s[18:19]
	v_cmp_lt_i32_e32 vcc, 0, v128
	s_mov_b64 s[20:21], s[18:19]
	v_mfma_f32_32x32x16_bf16 v[38:53], v[38:41], v[70:73], 0
	s_waitcnt lgkmcnt(1)
	v_mfma_f32_32x32x16_bf16 v[54:69], v[138:141], v[74:77], v[54:69]
	s_waitcnt lgkmcnt(0)
	v_mfma_f32_32x32x16_bf16 v[38:53], v[142:145], v[74:77], v[38:53]
	ds_read_b128 v[138:141], v134 offset:64
	ds_read_b128 v[142:145], v134 offset:6720
	s_waitcnt lgkmcnt(1)
	v_mfma_f32_32x32x16_bf16 v[54:69], v[138:141], v[78:81], v[54:69]
	s_waitcnt lgkmcnt(0)
	v_mfma_f32_32x32x16_bf16 v[38:53], v[142:145], v[78:81], v[38:53]
	ds_read_b128 v[138:141], v134 offset:96
	ds_read_b128 v[142:145], v134 offset:6752
	s_waitcnt lgkmcnt(1)
	v_mfma_f32_32x32x16_bf16 v[54:69], v[138:141], v[82:85], v[54:69]
	s_waitcnt lgkmcnt(0)
	v_mfma_f32_32x32x16_bf16 v[38:53], v[142:145], v[82:85], v[38:53]
	ds_read_b128 v[138:141], v134 offset:128
	ds_read_b128 v[142:145], v134 offset:6784
	s_waitcnt lgkmcnt(1)
	v_mfma_f32_32x32x16_bf16 v[54:69], v[138:141], v[86:89], v[54:69]
	s_waitcnt lgkmcnt(0)
	v_mfma_f32_32x32x16_bf16 v[38:53], v[142:145], v[86:89], v[38:53]
	ds_read_b128 v[138:141], v134 offset:160
	ds_read_b128 v[142:145], v134 offset:6816
	s_waitcnt lgkmcnt(1)
	v_mfma_f32_32x32x16_bf16 v[54:69], v[138:141], v[90:93], v[54:69]
	s_waitcnt lgkmcnt(0)
	v_mfma_f32_32x32x16_bf16 v[38:53], v[142:145], v[90:93], v[38:53]
	s_nop 9
	v_fma_f32 v0, v54, s88, v146
	v_fma_f32 v1, v55, s88, v146
	v_cndmask_b32_e32 v4, v196, v1, vcc
	v_cmp_lt_i32_e32 vcc, -1, v128
	s_nop 1
	v_cndmask_b32_e32 v143, v196, v0, vcc
	v_pk_fma_f32 v[0:1], v[38:39], s[88:89], v[146:147] op_sel_hi:[1,0,0]
	v_cmp_lt_i32_e32 vcc, 32, v128
	s_nop 1
	v_cndmask_b32_e32 v142, v196, v1, vcc
	v_cmp_lt_i32_e32 vcc, 31, v128
	s_nop 1
	v_cndmask_b32_e32 v145, v196, v0, vcc
	v_pk_fma_f32 v[0:1], v[56:57], s[88:89], v[146:147] op_sel_hi:[1,0,0]
	v_cmp_lt_i32_e32 vcc, 2, v128
	s_nop 1
	v_cndmask_b32_e32 v130, v196, v1, vcc
	v_cmp_lt_i32_e32 vcc, 1, v128
	s_nop 1
	v_cndmask_b32_e32 v140, v196, v0, vcc
	v_pk_fma_f32 v[0:1], v[40:41], s[88:89], v[146:147] op_sel_hi:[1,0,0]
	v_cmp_lt_i32_e32 vcc, 34, v128
	s_nop 1
	v_cndmask_b32_e32 v139, v196, v1, vcc
	v_cmp_lt_i32_e32 vcc, 33, v128
	s_nop 1
	v_cndmask_b32_e32 v144, v196, v0, vcc
	v_pk_fma_f32 v[0:1], v[58:59], s[88:89], v[146:147] op_sel_hi:[1,0,0]
	v_cmp_lt_i32_e32 vcc, 8, v128
	s_nop 1
	v_cndmask_b32_e32 v56, v196, v1, vcc
	v_cmp_lt_i32_e32 vcc, 7, v128
	s_nop 1
	v_cndmask_b32_e32 v138, v196, v0, vcc
	v_pk_fma_f32 v[0:1], v[42:43], s[88:89], v[146:147] op_sel_hi:[1,0,0]
	v_cmp_lt_i32_e32 vcc, 40, v128
	s_nop 1
	v_cndmask_b32_e32 v131, v196, v1, vcc
	v_cmp_lt_i32_e32 vcc, 39, v128
	s_nop 1
	v_cndmask_b32_e32 v141, v196, v0, vcc
	v_pk_fma_f32 v[0:1], v[60:61], s[88:89], v[146:147] op_sel_hi:[1,0,0]
	v_cmp_lt_i32_e32 vcc, 10, v128
	s_nop 1
	v_cndmask_b32_e32 v54, v196, v1, vcc
	v_cmp_lt_i32_e32 vcc, 9, v128
	s_nop 1
	v_cndmask_b32_e32 v58, v196, v0, vcc
	v_pk_fma_f32 v[0:1], v[44:45], s[88:89], v[146:147] op_sel_hi:[1,0,0]
	v_cmp_lt_i32_e32 vcc, 42, v128
	s_nop 1
	v_cndmask_b32_e32 v57, v196, v1, vcc
	v_cmp_lt_i32_e32 vcc, 41, v128
	s_nop 1
	v_cndmask_b32_e32 v60, v196, v0, vcc
	v_pk_fma_f32 v[0:1], v[62:63], s[88:89], v[146:147] op_sel_hi:[1,0,0]
	v_cmp_lt_i32_e32 vcc, 16, v128
	s_nop 1
	v_cndmask_b32_e32 v43, v196, v1, vcc
	v_cmp_lt_i32_e32 vcc, 15, v128
	s_nop 1
	v_cndmask_b32_e32 v55, v196, v0, vcc
	v_pk_fma_f32 v[0:1], v[46:47], s[88:89], v[146:147] op_sel_hi:[1,0,0]
	v_cmp_lt_i32_e32 vcc, 48, v128
	s_nop 1
	v_cndmask_b32_e32 v47, v196, v1, vcc
	v_cmp_lt_i32_e32 vcc, 47, v128
	s_nop 1
	v_cndmask_b32_e32 v59, v196, v0, vcc
	v_pk_fma_f32 v[0:1], v[64:65], s[88:89], v[146:147] op_sel_hi:[1,0,0]
	v_cmp_lt_i32_e32 vcc, 18, v128
	s_nop 1
	v_cndmask_b32_e32 v39, v196, v1, vcc
	v_cmp_lt_i32_e32 vcc, 17, v128
	s_nop 1
	v_cndmask_b32_e32 v45, v196, v0, vcc
	v_pk_fma_f32 v[0:1], v[48:49], s[88:89], v[146:147] op_sel_hi:[1,0,0]
	v_cmp_lt_i32_e32 vcc, 50, v128
	v_max_f32_e32 v49, v4, v142
	v_max3_f32 v49, v143, v145, v49
	v_cndmask_b32_e32 v44, v196, v1, vcc
	v_cmp_lt_i32_e32 vcc, 49, v128
	s_nop 1
	v_cndmask_b32_e32 v48, v196, v0, vcc
	v_pk_fma_f32 v[0:1], v[66:67], s[88:89], v[146:147] op_sel_hi:[1,0,0]
	v_cmp_lt_i32_e32 vcc, 24, v128
	s_nop 1
	v_cndmask_b32_e32 v3, v196, v1, vcc
	v_cmp_lt_i32_e32 vcc, 23, v128
	s_nop 1
	v_cndmask_b32_e32 v41, v196, v0, vcc
	v_pk_fma_f32 v[0:1], v[50:51], s[88:89], v[146:147] op_sel_hi:[1,0,0]
	v_cmp_lt_i32_e32 vcc, 56, v128
	v_pk_fma_f32 v[50:51], v[68:69], s[88:89], v[146:147] op_sel_hi:[1,0,0]
	s_nop 0
	v_cndmask_b32_e32 v40, v196, v1, vcc
	v_cmp_lt_i32_e32 vcc, 55, v128
	s_nop 1
	v_cndmask_b32_e32 v46, v196, v0, vcc
	v_cmp_lt_i32_e32 vcc, 26, v128
	s_nop 1
	v_cndmask_b32_e32 v0, v196, v51, vcc
	v_cmp_lt_i32_e32 vcc, 25, v128
	s_nop 1
	v_cndmask_b32_e32 v38, v196, v50, vcc
	v_pk_fma_f32 v[50:51], v[52:53], s[88:89], v[146:147] op_sel_hi:[1,0,0]
	v_cmp_lt_i32_e32 vcc, 58, v128
	s_nop 1
	v_cndmask_b32_e32 v1, v196, v51, vcc
	v_cmp_lt_i32_e32 vcc, 57, v128
	v_max_f32_e32 v51, v130, v139
	s_nop 0
	v_cndmask_b32_e32 v42, v196, v50, vcc
	v_max_f32_e32 v50, v140, v144
	v_max3_f32 v49, v49, v50, v51
	v_max_f32_e32 v50, v138, v141
	v_max_f32_e32 v51, v56, v131
	v_max3_f32 v49, v49, v50, v51
	v_max_f32_e32 v50, v58, v60
	v_max_f32_e32 v51, v54, v57
	v_max3_f32 v49, v49, v50, v51
	v_max_f32_e32 v50, v55, v59
	v_max_f32_e32 v51, v43, v47
	v_max3_f32 v49, v49, v50, v51
	v_max_f32_e32 v50, v45, v48
	v_max_f32_e32 v51, v39, v44
	v_max3_f32 v49, v49, v50, v51
	v_max_f32_e32 v50, v41, v46
	v_max_f32_e32 v51, v3, v40
	v_max3_f32 v49, v49, v50, v51
	v_max_f32_e32 v50, v38, v42
	v_max_f32_e32 v51, v0, v1
	v_max3_f32 v49, v49, v50, v51
	v_mov_b32_e32 v50, v49
	s_and_b64 vcc, exec, s[18:19]
	s_waitcnt lgkmcnt(0)
	s_nop 1
	v_permlane32_swap_b32_e32 v50, v49
	v_max_f32_e32 v49, v49, v50
	v_cmp_lt_f32_e64 s[46:47], s38, v49
	s_cbranch_vccnz .LBB0_161
	s_cmp_lg_u64 s[46:47], 0
	s_cselect_b64 s[20:21], -1, 0

.LBB0_173:
	ds_read_b128 v[0:3], v134 offset:19968
	ds_read_b128 v[38:41], v134 offset:13312
	ds_read_b128 v[138:141], v134 offset:13344
	s_cmp_eq_u32 s25, 0
	s_cselect_b64 s[18:19], -1, 0
	v_add_u32_e32 v147, 64, v128
	s_waitcnt lgkmcnt(1)
	v_mfma_f32_32x32x16_bf16 v[54:69], v[38:41], v[70:73], 0
	v_cndmask_b32_e64 v146, -v137, v195, s[18:19]
	v_cmp_lt_i32_e32 vcc, 0, v147
	s_mov_b64 s[20:21], s[18:19]
	v_mfma_f32_32x32x16_bf16 v[38:53], v[0:3], v[70:73], 0
	ds_read_b128 v[0:3], v134 offset:20000
	s_waitcnt lgkmcnt(1)
	v_mfma_f32_32x32x16_bf16 v[54:69], v[138:141], v[74:77], v[54:69]
	s_waitcnt lgkmcnt(0)
	v_mfma_f32_32x32x16_bf16 v[38:53], v[0:3], v[74:77], v[38:53]
	ds_read_b128 v[0:3], v134 offset:13376
	ds_read_b128 v[138:141], v134 offset:20032
	s_waitcnt lgkmcnt(1)
	v_mfma_f32_32x32x16_bf16 v[54:69], v[0:3], v[78:81], v[54:69]
	s_waitcnt lgkmcnt(0)
	v_mfma_f32_32x32x16_bf16 v[38:53], v[138:141], v[78:81], v[38:53]
	ds_read_b128 v[0:3], v134 offset:13408
	ds_read_b128 v[138:141], v134 offset:20064
	s_waitcnt lgkmcnt(1)
	v_mfma_f32_32x32x16_bf16 v[54:69], v[0:3], v[82:85], v[54:69]
	s_waitcnt lgkmcnt(0)
	v_mfma_f32_32x32x16_bf16 v[38:53], v[138:141], v[82:85], v[38:53]
	ds_read_b128 v[0:3], v134 offset:13440
	ds_read_b128 v[138:141], v134 offset:20096
	s_waitcnt lgkmcnt(1)
	v_mfma_f32_32x32x16_bf16 v[54:69], v[0:3], v[86:89], v[54:69]
	s_waitcnt lgkmcnt(0)
	v_mfma_f32_32x32x16_bf16 v[38:53], v[138:141], v[86:89], v[38:53]
	ds_read_b128 v[0:3], v134 offset:13472
	ds_read_b128 v[138:141], v134 offset:20128
	s_waitcnt lgkmcnt(1)
	v_mfma_f32_32x32x16_bf16 v[54:69], v[0:3], v[90:93], v[54:69]
	s_waitcnt lgkmcnt(0)
	v_mfma_f32_32x32x16_bf16 v[38:53], v[138:141], v[90:93], v[38:53]
	s_nop 9
	v_fma_f32 v0, v54, s88, v146
	v_fma_f32 v1, v55, s88, v146
	v_cndmask_b32_e32 v4, v196, v1, vcc
	v_cmp_lt_i32_e32 vcc, -1, v147
	s_nop 1
	v_cndmask_b32_e32 v143, v196, v0, vcc
	v_pk_fma_f32 v[0:1], v[38:39], s[88:89], v[146:147] op_sel_hi:[1,0,0]
	v_cmp_lt_i32_e32 vcc, 32, v147
	s_nop 1
	v_cndmask_b32_e32 v142, v196, v1, vcc
	v_cmp_lt_i32_e32 vcc, 31, v147
	s_nop 1
	v_cndmask_b32_e32 v145, v196, v0, vcc
	v_pk_fma_f32 v[0:1], v[56:57], s[88:89], v[146:147] op_sel_hi:[1,0,0]
	v_cmp_lt_i32_e32 vcc, 2, v147
	s_nop 1
	v_cndmask_b32_e32 v130, v196, v1, vcc
	v_cmp_lt_i32_e32 vcc, 1, v147
	s_nop 1
	v_cndmask_b32_e32 v140, v196, v0, vcc
	v_pk_fma_f32 v[0:1], v[40:41], s[88:89], v[146:147] op_sel_hi:[1,0,0]
	v_cmp_lt_i32_e32 vcc, 34, v147
	s_nop 1
	v_cndmask_b32_e32 v139, v196, v1, vcc
	v_cmp_lt_i32_e32 vcc, 33, v147
	s_nop 1
	v_cndmask_b32_e32 v144, v196, v0, vcc
	v_pk_fma_f32 v[0:1], v[58:59], s[88:89], v[146:147] op_sel_hi:[1,0,0]
	v_cmp_lt_i32_e32 vcc, 8, v147
	s_nop 1
	v_cndmask_b32_e32 v56, v196, v1, vcc
	v_cmp_lt_i32_e32 vcc, 7, v147
	s_nop 1
	v_cndmask_b32_e32 v138, v196, v0, vcc
	v_pk_fma_f32 v[0:1], v[42:43], s[88:89], v[146:147] op_sel_hi:[1,0,0]
	v_cmp_lt_i32_e32 vcc, 40, v147
	s_nop 1
	v_cndmask_b32_e32 v131, v196, v1, vcc
	v_cmp_lt_i32_e32 vcc, 39, v147
	s_nop 1
	v_cndmask_b32_e32 v141, v196, v0, vcc
	v_pk_fma_f32 v[0:1], v[60:61], s[88:89], v[146:147] op_sel_hi:[1,0,0]
	v_cmp_lt_i32_e32 vcc, 10, v147
	s_nop 1
	v_cndmask_b32_e32 v54, v196, v1, vcc
	v_cmp_lt_i32_e32 vcc, 9, v147
	s_nop 1
	v_cndmask_b32_e32 v58, v196, v0, vcc
	v_pk_fma_f32 v[0:1], v[44:45], s[88:89], v[146:147] op_sel_hi:[1,0,0]
	v_cmp_lt_i32_e32 vcc, 42, v147
	s_nop 1
	v_cndmask_b32_e32 v57, v196, v1, vcc
	v_cmp_lt_i32_e32 vcc, 41, v147
	s_nop 1
	v_cndmask_b32_e32 v60, v196, v0, vcc
	v_pk_fma_f32 v[0:1], v[62:63], s[88:89], v[146:147] op_sel_hi:[1,0,0]
	v_cmp_lt_i32_e32 vcc, 16, v147
	s_nop 1
	v_cndmask_b32_e32 v42, v196, v1, vcc
	v_cmp_lt_i32_e32 vcc, 15, v147
	s_nop 1
	v_cndmask_b32_e32 v55, v196, v0, vcc
	v_pk_fma_f32 v[0:1], v[46:47], s[88:89], v[146:147] op_sel_hi:[1,0,0]
	v_cmp_lt_i32_e32 vcc, 48, v147
	s_nop 1
	v_cndmask_b32_e32 v46, v196, v1, vcc
	v_cmp_lt_i32_e32 vcc, 47, v147
	s_nop 1
	v_cndmask_b32_e32 v59, v196, v0, vcc
	v_pk_fma_f32 v[0:1], v[64:65], s[88:89], v[146:147] op_sel_hi:[1,0,0]
	v_cmp_lt_i32_e32 vcc, 18, v147
	s_nop 1
	v_cndmask_b32_e32 v38, v196, v1, vcc
	v_cmp_lt_i32_e32 vcc, 17, v147
	s_nop 1
	v_cndmask_b32_e32 v44, v196, v0, vcc
	v_pk_fma_f32 v[0:1], v[48:49], s[88:89], v[146:147] op_sel_hi:[1,0,0]
	v_cmp_lt_i32_e32 vcc, 50, v147
	v_pk_fma_f32 v[48:49], v[68:69], s[88:89], v[146:147] op_sel_hi:[1,0,0]
	s_nop 0
	v_cndmask_b32_e32 v43, v196, v1, vcc
	v_cmp_lt_i32_e32 vcc, 49, v147
	s_nop 1
	v_cndmask_b32_e32 v47, v196, v0, vcc
	v_pk_fma_f32 v[0:1], v[66:67], s[88:89], v[146:147] op_sel_hi:[1,0,0]
	v_cmp_lt_i32_e32 vcc, 24, v147
	s_nop 1
	v_cndmask_b32_e32 v2, v196, v1, vcc
	v_cmp_lt_i32_e32 vcc, 23, v147
	s_nop 1
	v_cndmask_b32_e32 v40, v196, v0, vcc
	v_pk_fma_f32 v[0:1], v[50:51], s[88:89], v[146:147] op_sel_hi:[1,0,0]
	v_cmp_lt_i32_e32 vcc, 56, v147
	v_max_f32_e32 v50, v130, v139
	s_nop 0
	v_cndmask_b32_e32 v39, v196, v1, vcc
	v_cmp_lt_i32_e32 vcc, 55, v147
	s_nop 1
	v_cndmask_b32_e32 v45, v196, v0, vcc
	v_cmp_lt_i32_e32 vcc, 26, v147
	s_nop 1
	v_cndmask_b32_e32 v0, v196, v49, vcc
	v_cmp_lt_i32_e32 vcc, 25, v147
	s_nop 1
	v_cndmask_b32_e32 v3, v196, v48, vcc
	v_pk_fma_f32 v[48:49], v[52:53], s[88:89], v[146:147] op_sel_hi:[1,0,0]
	v_cmp_lt_i32_e32 vcc, 58, v147
	s_nop 1
	v_cndmask_b32_e32 v1, v196, v49, vcc
	v_cmp_lt_i32_e32 vcc, 57, v147
	v_max_f32_e32 v49, v140, v144
	s_nop 0
	v_cndmask_b32_e32 v41, v196, v48, vcc
	v_max_f32_e32 v48, v4, v142
	v_max3_f32 v48, v143, v145, v48
	v_max3_f32 v48, v48, v49, v50
	v_max_f32_e32 v49, v138, v141
	v_max_f32_e32 v50, v56, v131
	v_max3_f32 v48, v48, v49, v50
	v_max_f32_e32 v49, v58, v60
	v_max_f32_e32 v50, v54, v57
	v_max3_f32 v48, v48, v49, v50
	v_max_f32_e32 v49, v55, v59
	v_max_f32_e32 v50, v42, v46
	v_max3_f32 v48, v48, v49, v50
	v_max_f32_e32 v49, v44, v47
	v_max_f32_e32 v50, v38, v43
	v_max3_f32 v48, v48, v49, v50
	v_max_f32_e32 v49, v40, v45
	v_max_f32_e32 v50, v2, v39
	v_max3_f32 v48, v48, v49, v50
	v_max_f32_e32 v49, v3, v41
	v_max_f32_e32 v50, v0, v1
	v_max3_f32 v48, v48, v49, v50
	v_mov_b32_e32 v49, v48
	s_and_b64 vcc, exec, s[18:19]
	s_waitcnt lgkmcnt(0)
	s_nop 1
	v_permlane32_swap_b32_e32 v49, v48
	v_max_f32_e32 v48, v48, v49
	v_cmp_lt_f32_e64 s[46:47], s38, v48
	s_cbranch_vccnz .LBB0_175
	s_cmp_lg_u64 s[46:47], 0
	s_cselect_b64 s[20:21], -1, 0

.LBB0_194:
	v_add_u32_e32 v3, s4, v134
	ds_read_b128 v[38:41], v3 offset:6656
	ds_read_b128 v[42:45], v3
	ds_read_b128 v[120:123], v3 offset:32
	ds_read_b128 v[124:127], v3 offset:6688
	ds_read_b128 v[204:207], v3 offset:64
	ds_read_b128 v[208:211], v3 offset:6720
	ds_read_b128 v[212:215], v3 offset:96
	ds_read_b128 v[216:219], v3 offset:6752
	ds_read_b128 v[220:223], v3 offset:128
	ds_read_b128 v[224:227], v3 offset:6784
	ds_read_b128 v[228:231], v3 offset:160
	ds_read_b128 v[232:235], v3 offset:6816
	s_cmp_eq_u32 s7, s23
	s_cselect_b64 s[18:19], -1, 0
	s_waitcnt lgkmcnt(10)
	v_mfma_f32_32x32x16_bf16 v[54:69], v[42:45], v[70:73], 0
	v_cndmask_b32_e64 v4, -v137, v195, s[18:19]
	s_and_b64 vcc, exec, s[18:19]
	s_mov_b64 s[20:21], s[18:19]
	v_mfma_f32_32x32x16_bf16 v[38:53], v[38:41], v[70:73], 0
	s_waitcnt lgkmcnt(9)
	v_mfma_f32_32x32x16_bf16 v[54:69], v[120:123], v[74:77], v[54:69]
	s_waitcnt lgkmcnt(8)
	v_mfma_f32_32x32x16_bf16 v[38:53], v[124:127], v[74:77], v[38:53]
	s_waitcnt lgkmcnt(7)
	v_mfma_f32_32x32x16_bf16 v[54:69], v[204:207], v[78:81], v[54:69]
	s_waitcnt lgkmcnt(6)
	v_mfma_f32_32x32x16_bf16 v[38:53], v[208:211], v[78:81], v[38:53]
	s_waitcnt lgkmcnt(5)
	v_mfma_f32_32x32x16_bf16 v[54:69], v[212:215], v[82:85], v[54:69]
	s_waitcnt lgkmcnt(4)
	v_mfma_f32_32x32x16_bf16 v[38:53], v[216:219], v[82:85], v[38:53]
	s_waitcnt lgkmcnt(3)
	v_mfma_f32_32x32x16_bf16 v[54:69], v[220:223], v[86:89], v[54:69]
	s_waitcnt lgkmcnt(2)
	v_mfma_f32_32x32x16_bf16 v[38:53], v[224:227], v[86:89], v[38:53]
	s_waitcnt lgkmcnt(1)
	v_mfma_f32_32x32x16_bf16 v[54:69], v[228:231], v[90:93], v[54:69]
	s_waitcnt lgkmcnt(0)
	v_mfma_f32_32x32x16_bf16 v[38:53], v[232:235], v[90:93], v[38:53]
	s_nop 9
	v_fma_f32 v128, v54, s88, v4
	v_fma_f32 v129, v55, s88, v4
	v_fma_f32 v124, v56, s88, v4
	v_fma_f32 v125, v57, s88, v4
	v_fma_f32 v120, v58, s88, v4
	v_fma_f32 v121, v59, s88, v4
	v_pk_fma_f32 v[58:59], v[60:61], s[88:89], v[4:5] op_sel_hi:[1,0,0]
	v_pk_fma_f32 v[54:55], v[62:63], s[88:89], v[4:5] op_sel_hi:[1,0,0]
	v_pk_fma_f32 v[130:131], v[38:39], s[88:89], v[4:5] op_sel_hi:[1,0,0]
	v_pk_fma_f32 v[126:127], v[40:41], s[88:89], v[4:5] op_sel_hi:[1,0,0]
	v_max_f32_e32 v3, v129, v131
	v_pk_fma_f32 v[122:123], v[42:43], s[88:89], v[4:5] op_sel_hi:[1,0,0]
	v_pk_fma_f32 v[60:61], v[44:45], s[88:89], v[4:5] op_sel_hi:[1,0,0]
	v_pk_fma_f32 v[56:57], v[46:47], s[88:89], v[4:5] op_sel_hi:[1,0,0]
	v_pk_fma_f32 v[46:47], v[64:65], s[88:89], v[4:5] op_sel_hi:[1,0,0]
	v_pk_fma_f32 v[48:49], v[48:49], s[88:89], v[4:5] op_sel_hi:[1,0,0]
	v_pk_fma_f32 v[42:43], v[66:67], s[88:89], v[4:5] op_sel_hi:[1,0,0]
	v_pk_fma_f32 v[44:45], v[50:51], s[88:89], v[4:5] op_sel_hi:[1,0,0]
	v_pk_fma_f32 v[38:39], v[68:69], s[88:89], v[4:5] op_sel_hi:[1,0,0]
	v_pk_fma_f32 v[40:41], v[52:53], s[88:89], v[4:5] op_sel_hi:[1,0,0]
	v_max3_f32 v3, v128, v130, v3
	v_max_f32_e32 v4, v124, v126
	v_max_f32_e32 v50, v125, v127
	v_max3_f32 v3, v3, v4, v50
	v_max_f32_e32 v4, v120, v122
	v_max_f32_e32 v50, v121, v123
	v_max3_f32 v3, v3, v4, v50
	v_max_f32_e32 v4, v58, v60
	v_max_f32_e32 v50, v59, v61
	v_max3_f32 v3, v3, v4, v50
	v_max_f32_e32 v4, v54, v56
	v_max_f32_e32 v50, v55, v57
	v_max3_f32 v3, v3, v4, v50
	v_max_f32_e32 v4, v46, v48
	v_max_f32_e32 v50, v47, v49
	v_max3_f32 v3, v3, v4, v50
	v_max_f32_e32 v4, v42, v44
	v_max_f32_e32 v50, v43, v45
	v_max3_f32 v3, v3, v4, v50
	v_max_f32_e32 v4, v38, v40
	v_max_f32_e32 v50, v39, v41
	v_max3_f32 v3, v3, v4, v50
	v_mov_b32_e32 v4, v3
	s_waitcnt lgkmcnt(0)
	s_nop 1
	v_permlane32_swap_b32_e32 v4, v3
	v_max_f32_e32 v3, v3, v4
	v_cmp_lt_f32_e64 s[46:47], s38, v3
	s_cbranch_vccnz .LBB0_196
	s_cmp_lg_u64 s[46:47], 0
	s_cselect_b64 s[20:21], -1, 0

.LBB0_208:
	v_add_u32_e32 v3, s22, v134
	ds_read_b128 v[38:41], v3 offset:6656
	ds_read_b128 v[42:45], v3
	ds_read_b128 v[120:123], v3 offset:32
	ds_read_b128 v[124:127], v3 offset:6688
	ds_read_b128 v[204:207], v3 offset:64
	ds_read_b128 v[208:211], v3 offset:6720
	ds_read_b128 v[212:215], v3 offset:96
	ds_read_b128 v[216:219], v3 offset:6752
	ds_read_b128 v[220:223], v3 offset:128
	ds_read_b128 v[224:227], v3 offset:6784
	ds_read_b128 v[228:231], v3 offset:160
	ds_read_b128 v[232:235], v3 offset:6816
	s_cmp_eq_u32 s25, s23
	s_cselect_b64 s[18:19], -1, 0
	s_waitcnt lgkmcnt(10)
	v_mfma_f32_32x32x16_bf16 v[54:69], v[42:45], v[70:73], 0
	v_cndmask_b32_e64 v4, -v137, v195, s[18:19]
	s_and_b64 vcc, exec, s[18:19]
	s_mov_b64 s[20:21], s[18:19]
	v_mfma_f32_32x32x16_bf16 v[38:53], v[38:41], v[70:73], 0
	s_waitcnt lgkmcnt(9)
	v_mfma_f32_32x32x16_bf16 v[54:69], v[120:123], v[74:77], v[54:69]
	s_waitcnt lgkmcnt(8)
	v_mfma_f32_32x32x16_bf16 v[38:53], v[124:127], v[74:77], v[38:53]
	s_waitcnt lgkmcnt(7)
	v_mfma_f32_32x32x16_bf16 v[54:69], v[204:207], v[78:81], v[54:69]
	s_waitcnt lgkmcnt(6)
	v_mfma_f32_32x32x16_bf16 v[38:53], v[208:211], v[78:81], v[38:53]
	s_waitcnt lgkmcnt(5)
	v_mfma_f32_32x32x16_bf16 v[54:69], v[212:215], v[82:85], v[54:69]
	s_waitcnt lgkmcnt(4)
	v_mfma_f32_32x32x16_bf16 v[38:53], v[216:219], v[82:85], v[38:53]
	s_waitcnt lgkmcnt(3)
	v_mfma_f32_32x32x16_bf16 v[54:69], v[220:223], v[86:89], v[54:69]
	s_waitcnt lgkmcnt(2)
	v_mfma_f32_32x32x16_bf16 v[38:53], v[224:227], v[86:89], v[38:53]
	s_waitcnt lgkmcnt(1)
	v_mfma_f32_32x32x16_bf16 v[54:69], v[228:231], v[90:93], v[54:69]
	s_waitcnt lgkmcnt(0)
	v_mfma_f32_32x32x16_bf16 v[38:53], v[232:235], v[90:93], v[38:53]
	s_nop 9
	v_fma_f32 v128, v54, s88, v4
	v_fma_f32 v129, v55, s88, v4
	v_fma_f32 v124, v56, s88, v4
	v_fma_f32 v125, v57, s88, v4
	v_fma_f32 v120, v58, s88, v4
	v_fma_f32 v121, v59, s88, v4
	v_pk_fma_f32 v[58:59], v[60:61], s[88:89], v[4:5] op_sel_hi:[1,0,0]
	v_pk_fma_f32 v[54:55], v[62:63], s[88:89], v[4:5] op_sel_hi:[1,0,0]
	v_pk_fma_f32 v[130:131], v[38:39], s[88:89], v[4:5] op_sel_hi:[1,0,0]
	v_pk_fma_f32 v[126:127], v[40:41], s[88:89], v[4:5] op_sel_hi:[1,0,0]
	v_max_f32_e32 v3, v129, v131
	v_pk_fma_f32 v[122:123], v[42:43], s[88:89], v[4:5] op_sel_hi:[1,0,0]
	v_pk_fma_f32 v[60:61], v[44:45], s[88:89], v[4:5] op_sel_hi:[1,0,0]
	v_pk_fma_f32 v[56:57], v[46:47], s[88:89], v[4:5] op_sel_hi:[1,0,0]
	v_pk_fma_f32 v[46:47], v[64:65], s[88:89], v[4:5] op_sel_hi:[1,0,0]
	v_pk_fma_f32 v[48:49], v[48:49], s[88:89], v[4:5] op_sel_hi:[1,0,0]
	v_pk_fma_f32 v[42:43], v[66:67], s[88:89], v[4:5] op_sel_hi:[1,0,0]
	v_pk_fma_f32 v[44:45], v[50:51], s[88:89], v[4:5] op_sel_hi:[1,0,0]
	v_pk_fma_f32 v[38:39], v[68:69], s[88:89], v[4:5] op_sel_hi:[1,0,0]
	v_pk_fma_f32 v[40:41], v[52:53], s[88:89], v[4:5] op_sel_hi:[1,0,0]
	v_max3_f32 v3, v128, v130, v3
	v_max_f32_e32 v4, v124, v126
	v_max_f32_e32 v50, v125, v127
	v_max3_f32 v3, v3, v4, v50
	v_max_f32_e32 v4, v120, v122
	v_max_f32_e32 v50, v121, v123
	v_max3_f32 v3, v3, v4, v50
	v_max_f32_e32 v4, v58, v60
	v_max_f32_e32 v50, v59, v61
	v_max3_f32 v3, v3, v4, v50
	v_max_f32_e32 v4, v54, v56
	v_max_f32_e32 v50, v55, v57
	v_max3_f32 v3, v3, v4, v50
	v_max_f32_e32 v4, v46, v48
	v_max_f32_e32 v50, v47, v49
	v_max3_f32 v3, v3, v4, v50
	v_max_f32_e32 v4, v42, v44
	v_max_f32_e32 v50, v43, v45
	v_max3_f32 v3, v3, v4, v50
	v_max_f32_e32 v4, v38, v40
	v_max_f32_e32 v50, v39, v41
	v_max3_f32 v3, v3, v4, v50
	v_mov_b32_e32 v4, v3
	s_waitcnt lgkmcnt(0)
	s_nop 1
	v_permlane32_swap_b32_e32 v4, v3
	v_max_f32_e32 v3, v3, v4
	v_cmp_lt_f32_e64 s[46:47], s38, v3
	s_cbranch_vccnz .LBB0_210
	s_cmp_lg_u64 s[46:47], 0
	s_cselect_b64 s[20:21], -1, 0

.LBB0_635:
	s_nop 4
	v_add_f32_e32 v159, v111, v1
	v_add_f32_e32 v1, v95, v237
	v_max3_f32 v4, v3, v161, v6
	v_max3_f32 v80, v164, v7, v165
	v_max3_f32 v4, v4, v160, v2
	v_max3_f32 v80, v80, v10, v168
	v_max3_f32 v4, v4, v11, v169
	v_max3_f32 v80, v80, v156, v172
	v_max3_f32 v4, v4, v157, v173
	v_max3_f32 v80, v80, v14, v170
	v_max3_f32 v4, v4, v15, v171
	v_max3_f32 v80, v80, v12, v166
	v_max3_f32 v4, v4, v13, v167
	v_max3_f32 v80, v80, v8, v162
	v_max3_f32 v4, v4, v9, v163
	v_max3_f32 v80, v80, v0, v158
	v_max3_f32 v4, v4, v159, v1
	v_max_f32_e32 v4, v4, v80
	v_mov_b32_e32 v80, v4
	s_andn2_b64 vcc, exec, s[18:19]
	s_waitcnt lgkmcnt(0)
	s_nop 1
	v_permlane32_swap_b32_e32 v80, v4
	v_max_f32_e32 v4, v4, v80
	v_cmp_lt_f32_e64 s[66:67], s38, v4
	s_cbranch_vccnz .LBB0_637
	s_cmp_lg_u64 s[66:67], 0
	s_cselect_b64 s[20:21], -1, 0

.LBB0_667:
	v_cvt_f32_i32_e32 v4, v180
	s_cmp_eq_u32 s23, -1
	s_cselect_b64 s[18:19], -1, 0
	v_cndmask_b32_e64 v3, v169, 0, s[18:19]
	v_fma_f32 v4, -v154, v4, -v3
	s_mov_b32 s20, 2.0
	v_add_f32_e32 v6, v153, v4
	s_mov_b32 s21, 0x40400000
	v_pk_fma_f32 v[98:99], v[154:155], s[20:21], v[4:5] op_sel_hi:[1,1,0]
	v_pk_fma_f32 v[82:83], v[154:155], s[20:21], v[6:7] op_sel_hi:[1,1,0]
	s_mov_b32 s20, 0x41200000
	s_mov_b32 s21, 0x41300000
	v_pk_fma_f32 v[102:103], v[154:155], s[20:21], v[4:5] op_sel_hi:[1,1,0]
	v_pk_fma_f32 v[86:87], v[154:155], s[20:21], v[6:7] op_sel_hi:[1,1,0]
	s_mov_b32 s20, 0x41800000
	s_mov_b32 s21, 0x41880000
	v_pk_fma_f32 v[104:105], v[154:155], s[20:21], v[4:5] op_sel_hi:[1,1,0]
	v_pk_fma_f32 v[88:89], v[154:155], s[20:21], v[6:7] op_sel_hi:[1,1,0]
	s_mov_b32 s20, 0x41900000
	s_mov_b32 s21, 0x41980000
	v_fma_f32 v80, 0, v154, v6
	v_add_f32_e32 v81, v154, v6
	v_pk_fma_f32 v[84:85], v[154:155], s[38:39], v[6:7] op_sel_hi:[1,1,0]
	v_pk_fma_f32 v[90:91], v[154:155], s[20:21], v[6:7] op_sel_hi:[1,1,0]
	v_pk_fma_f32 v[92:93], v[154:155], s[26:27], v[6:7] op_sel_hi:[1,1,0]
	v_pk_fma_f32 v[94:95], v[154:155], s[36:37], v[6:7] op_sel_hi:[1,1,0]
	ds_read_b128 v[6:9], v166 offset:4608
	ds_read_b128 v[10:13], v166
	ds_read_b128 v[206:209], v166 offset:32
	v_fma_f32 v96, 0, v154, v4
	v_add_f32_e32 v97, v154, v4
	v_pk_fma_f32 v[100:101], v[154:155], s[38:39], v[4:5] op_sel_hi:[1,1,0]
	v_pk_fma_f32 v[106:107], v[154:155], s[20:21], v[4:5] op_sel_hi:[1,1,0]
	v_pk_fma_f32 v[108:109], v[154:155], s[26:27], v[4:5] op_sel_hi:[1,1,0]
	v_pk_fma_f32 v[110:111], v[154:155], s[36:37], v[4:5] op_sel_hi:[1,1,0]
	s_waitcnt vmcnt(6) lgkmcnt(2)
	v_mfma_f32_32x32x16_bf16 v[80:95], v[6:9], v[112:115], v[80:95]
	ds_read_b128 v[6:9], v166 offset:4640
	v_cmp_lt_i32_e32 vcc, 0, v180
	s_mov_b64 s[20:21], s[18:19]
	s_waitcnt lgkmcnt(2)
	v_mfma_f32_32x32x16_bf16 v[96:111], v[10:13], v[112:115], v[96:111]
	s_waitcnt vmcnt(5) lgkmcnt(1)
	v_mfma_f32_32x32x16_bf16 v[96:111], v[206:209], v[116:119], v[96:111]
	s_waitcnt lgkmcnt(0)
	v_mfma_f32_32x32x16_bf16 v[80:95], v[6:9], v[116:119], v[80:95]
	ds_read_b128 v[6:9], v166 offset:64
	ds_read_b128 v[10:13], v166 offset:4672
	s_waitcnt vmcnt(4) lgkmcnt(1)
	v_mfma_f32_32x32x16_bf16 v[96:111], v[6:9], v[120:123], v[96:111]
	s_waitcnt lgkmcnt(0)
	v_mfma_f32_32x32x16_bf16 v[80:95], v[10:13], v[120:123], v[80:95]
	ds_read_b128 v[6:9], v166 offset:96
	ds_read_b128 v[10:13], v166 offset:4704
	s_waitcnt vmcnt(3) lgkmcnt(1)
	v_mfma_f32_32x32x16_bf16 v[96:111], v[6:9], v[124:127], v[96:111]
	s_waitcnt lgkmcnt(0)
	v_mfma_f32_32x32x16_bf16 v[80:95], v[10:13], v[124:127], v[80:95]
	s_nop 9
	v_cndmask_b32_e32 v4, v196, v97, vcc
	v_cmp_lt_i32_e32 vcc, -1, v180
	s_nop 1
	v_cndmask_b32_e32 v211, v196, v96, vcc
	v_cmp_lt_i32_e32 vcc, 32, v180
	s_nop 1
	v_cndmask_b32_e32 v210, v196, v81, vcc
	v_cmp_lt_i32_e32 vcc, 31, v180
	s_nop 1
	v_cndmask_b32_e32 v212, v196, v80, vcc
	v_cmp_lt_i32_e32 vcc, 2, v180
	s_nop 1
	v_cndmask_b32_e32 v206, v196, v99, vcc
	v_cmp_lt_i32_e32 vcc, 1, v180
	s_nop 1
	v_cndmask_b32_e32 v208, v196, v98, vcc
	v_cmp_lt_i32_e32 vcc, 34, v180
	s_nop 1
	v_cndmask_b32_e32 v207, v196, v83, vcc
	v_cmp_lt_i32_e32 vcc, 33, v180
	s_nop 1
	v_cndmask_b32_e32 v209, v196, v82, vcc
	v_cmp_lt_i32_e32 vcc, 8, v180
	s_nop 1
	v_cndmask_b32_e32 v97, v196, v101, vcc
	v_cmp_lt_i32_e32 vcc, 7, v180
	s_nop 1
	v_cndmask_b32_e32 v99, v196, v100, vcc
	v_cmp_lt_i32_e32 vcc, 40, v180
	s_nop 1
	v_cndmask_b32_e32 v98, v196, v85, vcc
	v_cmp_lt_i32_e32 vcc, 39, v180
	s_nop 1
	v_cndmask_b32_e32 v100, v196, v84, vcc
	v_cmp_lt_i32_e32 vcc, 10, v180
	s_nop 1
	v_cndmask_b32_e32 v84, v196, v103, vcc
	v_cmp_lt_i32_e32 vcc, 9, v180
	s_nop 1
	v_cndmask_b32_e32 v96, v196, v102, vcc
	v_cmp_lt_i32_e32 vcc, 42, v180
	s_nop 1
	v_cndmask_b32_e32 v87, v196, v87, vcc
	v_cmp_lt_i32_e32 vcc, 41, v180
	s_nop 1
	v_cndmask_b32_e32 v86, v196, v86, vcc
	v_cmp_lt_i32_e32 vcc, 16, v180
	s_nop 1
	v_cndmask_b32_e32 v80, v196, v105, vcc
	v_cmp_lt_i32_e32 vcc, 15, v180
	s_nop 1
	v_cndmask_b32_e32 v83, v196, v104, vcc
	v_cmp_lt_i32_e32 vcc, 48, v180
	s_nop 1
	v_cndmask_b32_e32 v82, v196, v89, vcc
	v_cmp_lt_i32_e32 vcc, 47, v180
	v_max_f32_e32 v89, v210, v210
	s_nop 0
	v_cndmask_b32_e32 v85, v196, v88, vcc
	v_cmp_lt_i32_e32 vcc, 18, v180
	v_max_f32_e32 v88, v4, v4
	v_max_f32_e32 v88, v88, v89
	v_cndmask_b32_e32 v12, v196, v107, vcc
	v_cmp_lt_i32_e32 vcc, 17, v180
	v_max_f32_e32 v89, v208, v208
	v_max3_f32 v88, v211, v212, v88
	v_cndmask_b32_e32 v15, v196, v106, vcc
	v_cmp_lt_i32_e32 vcc, 50, v180
	s_nop 1
	v_cndmask_b32_e32 v14, v196, v91, vcc
	v_cmp_lt_i32_e32 vcc, 49, v180
	v_max_f32_e32 v91, v207, v207
	s_nop 0
	v_cndmask_b32_e32 v81, v196, v90, vcc
	v_max_f32_e32 v90, v209, v209
	v_max_f32_e32 v89, v89, v90
	v_max_f32_e32 v90, v206, v206
	v_max_f32_e32 v90, v90, v91
	v_max3_f32 v88, v88, v89, v90
	v_max_f32_e32 v89, v99, v99
	v_max_f32_e32 v90, v100, v100
	v_max_f32_e32 v89, v89, v90
	v_max_f32_e32 v90, v97, v97
	v_max_f32_e32 v91, v98, v98
	v_max_f32_e32 v90, v90, v91
	v_max3_f32 v88, v88, v89, v90
	v_max_f32_e32 v89, v96, v96
	v_max_f32_e32 v90, v86, v86
	v_max_f32_e32 v89, v89, v90
	v_max_f32_e32 v90, v84, v84
	v_max_f32_e32 v91, v87, v87
	v_max_f32_e32 v90, v90, v91
	v_cmp_lt_i32_e32 vcc, 24, v180
	v_max3_f32 v88, v88, v89, v90
	v_max_f32_e32 v89, v83, v83
	v_max_f32_e32 v90, v85, v85
	v_cndmask_b32_e32 v8, v196, v109, vcc
	v_cmp_lt_i32_e32 vcc, 23, v180
	v_max_f32_e32 v89, v89, v90
	v_max_f32_e32 v90, v80, v80
	v_max_f32_e32 v91, v82, v82
	v_cndmask_b32_e32 v11, v196, v108, vcc
	v_cmp_lt_i32_e32 vcc, 56, v180
	v_max_f32_e32 v90, v90, v91
	v_max3_f32 v88, v88, v89, v90
	v_cndmask_b32_e32 v10, v196, v93, vcc
	v_cmp_lt_i32_e32 vcc, 55, v180
	v_max_f32_e32 v89, v15, v15
	v_max_f32_e32 v90, v81, v81
	v_cndmask_b32_e32 v13, v196, v92, vcc
	v_cmp_lt_i32_e32 vcc, 26, v180
	v_max_f32_e32 v89, v89, v90
	v_max_f32_e32 v90, v12, v12
	v_max_f32_e32 v91, v14, v14
	v_cndmask_b32_e32 v3, v196, v111, vcc
	v_cmp_lt_i32_e32 vcc, 25, v180
	v_max_f32_e32 v90, v90, v91
	v_max3_f32 v88, v88, v89, v90
	v_cndmask_b32_e32 v7, v196, v110, vcc
	v_cmp_lt_i32_e32 vcc, 58, v180
	v_max_f32_e32 v89, v11, v11
	v_max_f32_e32 v90, v13, v13
	v_cndmask_b32_e32 v6, v196, v95, vcc
	v_cmp_lt_i32_e32 vcc, 57, v180
	v_max_f32_e32 v89, v89, v90
	v_max_f32_e32 v90, v8, v8
	v_max_f32_e32 v91, v10, v10
	v_cndmask_b32_e32 v9, v196, v94, vcc
	v_max_f32_e32 v90, v90, v91
	v_max3_f32 v88, v88, v89, v90
	v_max_f32_e32 v89, v7, v7
	v_max_f32_e32 v90, v9, v9
	v_max_f32_e32 v89, v89, v90
	v_max_f32_e32 v90, v3, v3
	v_max_f32_e32 v91, v6, v6
	v_max_f32_e32 v90, v90, v91
	v_max3_f32 v88, v88, v89, v90
	v_mov_b32_e32 v89, v88
	s_and_b64 vcc, exec, s[18:19]
	s_waitcnt lgkmcnt(0)
	s_nop 1
	v_permlane32_swap_b32_e32 v89, v88
	v_max_f32_e32 v88, v88, v89
	v_cmp_lt_f32_e64 s[44:45], s38, v88
	s_cbranch_vccnz .LBB0_669
	s_cmp_lg_u64 s[44:45], 0
	s_cselect_b64 s[20:21], -1, 0

.LBB0_673:
	v_add_u32_e32 v212, 64, v180
	v_cvt_f32_i32_e32 v1, v212
	s_cmp_eq_u32 s23, 0
	s_cselect_b64 s[18:19], -1, 0
	v_cndmask_b32_e64 v0, v169, 0, s[18:19]
	v_fma_f32 v0, -v154, v1, -v0
	s_mov_b32 s20, 2.0
	v_add_f32_e32 v2, v153, v0
	s_mov_b32 s21, 0x40400000
	v_pk_fma_f32 v[98:99], v[154:155], s[20:21], v[0:1] op_sel_hi:[1,1,0]
	v_pk_fma_f32 v[82:83], v[154:155], s[20:21], v[2:3] op_sel_hi:[1,1,0]
	s_mov_b32 s20, 0x41200000
	s_mov_b32 s21, 0x41300000
	v_pk_fma_f32 v[102:103], v[154:155], s[20:21], v[0:1] op_sel_hi:[1,1,0]
	v_pk_fma_f32 v[86:87], v[154:155], s[20:21], v[2:3] op_sel_hi:[1,1,0]
	s_mov_b32 s20, 0x41800000
	s_mov_b32 s21, 0x41880000
	v_pk_fma_f32 v[104:105], v[154:155], s[20:21], v[0:1] op_sel_hi:[1,1,0]
	v_pk_fma_f32 v[88:89], v[154:155], s[20:21], v[2:3] op_sel_hi:[1,1,0]
	s_mov_b32 s20, 0x41900000
	s_mov_b32 s21, 0x41980000
	v_fma_f32 v96, 0, v154, v0
	v_fma_f32 v80, 0, v154, v2
	v_add_f32_e32 v97, v154, v0
	v_add_f32_e32 v81, v154, v2
	v_pk_fma_f32 v[100:101], v[154:155], s[38:39], v[0:1] op_sel_hi:[1,1,0]
	v_pk_fma_f32 v[84:85], v[154:155], s[38:39], v[2:3] op_sel_hi:[1,1,0]
	v_pk_fma_f32 v[106:107], v[154:155], s[20:21], v[0:1] op_sel_hi:[1,1,0]
	v_pk_fma_f32 v[90:91], v[154:155], s[20:21], v[2:3] op_sel_hi:[1,1,0]
	v_pk_fma_f32 v[108:109], v[154:155], s[26:27], v[0:1] op_sel_hi:[1,1,0]
	v_pk_fma_f32 v[92:93], v[154:155], s[26:27], v[2:3] op_sel_hi:[1,1,0]
	v_pk_fma_f32 v[110:111], v[154:155], s[36:37], v[0:1] op_sel_hi:[1,1,0]
	v_pk_fma_f32 v[94:95], v[154:155], s[36:37], v[2:3] op_sel_hi:[1,1,0]
	ds_read_b128 v[0:3], v166 offset:13824
	ds_read_b128 v[6:9], v166 offset:9216
	ds_read_b128 v[10:13], v166 offset:9248
	s_waitcnt vmcnt(6) lgkmcnt(1)
	v_mfma_f32_32x32x16_bf16 v[96:111], v[6:9], v[112:115], v[96:111]
	v_cmp_lt_i32_e32 vcc, 0, v212
	s_mov_b64 s[20:21], s[18:19]
	v_mfma_f32_32x32x16_bf16 v[80:95], v[0:3], v[112:115], v[80:95]
	ds_read_b128 v[0:3], v166 offset:13856
	s_waitcnt vmcnt(5) lgkmcnt(1)
	v_mfma_f32_32x32x16_bf16 v[96:111], v[10:13], v[116:119], v[96:111]
	s_waitcnt lgkmcnt(0)
	v_mfma_f32_32x32x16_bf16 v[80:95], v[0:3], v[116:119], v[80:95]
	ds_read_b128 v[0:3], v166 offset:9280
	ds_read_b128 v[6:9], v166 offset:13888
	s_waitcnt vmcnt(4) lgkmcnt(1)
	v_mfma_f32_32x32x16_bf16 v[96:111], v[0:3], v[120:123], v[96:111]
	s_waitcnt lgkmcnt(0)
	v_mfma_f32_32x32x16_bf16 v[80:95], v[6:9], v[120:123], v[80:95]
	ds_read_b128 v[0:3], v166 offset:9312
	ds_read_b128 v[6:9], v166 offset:13920
	s_waitcnt vmcnt(3) lgkmcnt(1)
	v_mfma_f32_32x32x16_bf16 v[96:111], v[0:3], v[124:127], v[96:111]
	s_waitcnt lgkmcnt(0)
	v_mfma_f32_32x32x16_bf16 v[80:95], v[6:9], v[124:127], v[80:95]
	s_nop 9
	v_cndmask_b32_e32 v4, v196, v97, vcc
	v_cmp_lt_i32_e32 vcc, -1, v212
	s_nop 1
	v_cndmask_b32_e32 v210, v196, v96, vcc
	v_cmp_lt_i32_e32 vcc, 32, v212
	s_nop 1
	v_cndmask_b32_e32 v209, v196, v81, vcc
	v_cmp_lt_i32_e32 vcc, 31, v212
	s_nop 1
	v_cndmask_b32_e32 v211, v196, v80, vcc
	v_cmp_lt_i32_e32 vcc, 2, v212
	s_nop 1
	v_cndmask_b32_e32 v99, v196, v99, vcc
	v_cmp_lt_i32_e32 vcc, 1, v212
	s_nop 1
	v_cndmask_b32_e32 v207, v196, v98, vcc
	v_cmp_lt_i32_e32 vcc, 34, v212
	s_nop 1
	v_cndmask_b32_e32 v206, v196, v83, vcc
	v_cmp_lt_i32_e32 vcc, 33, v212
	s_nop 1
	v_cndmask_b32_e32 v208, v196, v82, vcc
	v_cmp_lt_i32_e32 vcc, 8, v212
	s_nop 1
	v_cndmask_b32_e32 v96, v196, v101, vcc
	v_cmp_lt_i32_e32 vcc, 7, v212
	s_nop 1
	v_cndmask_b32_e32 v98, v196, v100, vcc
	v_cmp_lt_i32_e32 vcc, 40, v212
	s_nop 1
	v_cndmask_b32_e32 v97, v196, v85, vcc
	v_cmp_lt_i32_e32 vcc, 39, v212
	s_nop 1
	v_cndmask_b32_e32 v100, v196, v84, vcc
	v_cmp_lt_i32_e32 vcc, 10, v212
	s_nop 1
	v_cndmask_b32_e32 v81, v196, v103, vcc
	v_cmp_lt_i32_e32 vcc, 9, v212
	s_nop 1
	v_cndmask_b32_e32 v84, v196, v102, vcc
	v_cmp_lt_i32_e32 vcc, 42, v212
	s_nop 1
	v_cndmask_b32_e32 v83, v196, v87, vcc
	v_cmp_lt_i32_e32 vcc, 41, v212
	v_max_f32_e32 v87, v209, v209
	s_nop 0
	v_cndmask_b32_e32 v85, v196, v86, vcc
	v_cmp_lt_i32_e32 vcc, 16, v212
	v_max_f32_e32 v86, v4, v4
	v_max_f32_e32 v86, v86, v87
	v_cndmask_b32_e32 v13, v196, v105, vcc
	v_cmp_lt_i32_e32 vcc, 15, v212
	v_max_f32_e32 v87, v207, v207
	v_max3_f32 v86, v210, v211, v86
	v_cndmask_b32_e32 v80, v196, v104, vcc
	v_cmp_lt_i32_e32 vcc, 48, v212
	s_nop 1
	v_cndmask_b32_e32 v15, v196, v89, vcc
	v_cmp_lt_i32_e32 vcc, 47, v212
	v_max_f32_e32 v89, v206, v206
	s_nop 0
	v_cndmask_b32_e32 v82, v196, v88, vcc
	v_max_f32_e32 v88, v208, v208
	v_max_f32_e32 v87, v87, v88
	v_max_f32_e32 v88, v99, v99
	v_max_f32_e32 v88, v88, v89
	v_max3_f32 v86, v86, v87, v88
	v_max_f32_e32 v87, v98, v98
	v_max_f32_e32 v88, v100, v100
	v_max_f32_e32 v87, v87, v88
	v_max_f32_e32 v88, v96, v96
	v_max_f32_e32 v89, v97, v97
	v_cmp_lt_i32_e32 vcc, 18, v212
	v_max_f32_e32 v88, v88, v89
	v_max3_f32 v86, v86, v87, v88
	v_cndmask_b32_e32 v9, v196, v107, vcc
	v_cmp_lt_i32_e32 vcc, 17, v212
	v_max_f32_e32 v87, v84, v84
	v_max_f32_e32 v88, v85, v85
	v_cndmask_b32_e32 v12, v196, v106, vcc
	v_cmp_lt_i32_e32 vcc, 50, v212
	v_max_f32_e32 v87, v87, v88
	v_max_f32_e32 v88, v81, v81
	v_max_f32_e32 v89, v83, v83
	v_cndmask_b32_e32 v11, v196, v91, vcc
	v_cmp_lt_i32_e32 vcc, 49, v212
	v_max_f32_e32 v88, v88, v89
	v_max3_f32 v86, v86, v87, v88
	v_cndmask_b32_e32 v14, v196, v90, vcc
	v_cmp_lt_i32_e32 vcc, 24, v212
	v_max_f32_e32 v87, v80, v80
	v_max_f32_e32 v88, v82, v82
	v_cndmask_b32_e32 v3, v196, v109, vcc
	v_cmp_lt_i32_e32 vcc, 23, v212
	v_max_f32_e32 v87, v87, v88
	v_max_f32_e32 v88, v13, v13
	v_max_f32_e32 v89, v15, v15
	v_cndmask_b32_e32 v8, v196, v108, vcc
	v_cmp_lt_i32_e32 vcc, 56, v212
	v_max_f32_e32 v88, v88, v89
	v_max3_f32 v86, v86, v87, v88
	v_cndmask_b32_e32 v7, v196, v93, vcc
	v_cmp_lt_i32_e32 vcc, 55, v212
	v_max_f32_e32 v87, v12, v12
	v_max_f32_e32 v88, v14, v14
	v_cndmask_b32_e32 v10, v196, v92, vcc
	v_cmp_lt_i32_e32 vcc, 26, v212
	v_max_f32_e32 v87, v87, v88
	v_max_f32_e32 v88, v9, v9
	v_max_f32_e32 v89, v11, v11
	v_cndmask_b32_e32 v0, v196, v111, vcc
	v_cmp_lt_i32_e32 vcc, 25, v212
	v_max_f32_e32 v88, v88, v89
	v_max3_f32 v86, v86, v87, v88
	v_cndmask_b32_e32 v2, v196, v110, vcc
	v_cmp_lt_i32_e32 vcc, 58, v212
	v_max_f32_e32 v87, v8, v8
	v_max_f32_e32 v88, v10, v10
	v_cndmask_b32_e32 v1, v196, v95, vcc
	v_cmp_lt_i32_e32 vcc, 57, v212
	v_max_f32_e32 v87, v87, v88
	v_max_f32_e32 v88, v3, v3
	v_max_f32_e32 v89, v7, v7
	v_cndmask_b32_e32 v6, v196, v94, vcc
	v_max_f32_e32 v88, v88, v89
	v_max3_f32 v86, v86, v87, v88
	v_max_f32_e32 v87, v2, v2
	v_max_f32_e32 v88, v6, v6
	v_max_f32_e32 v87, v87, v88
	v_max_f32_e32 v88, v0, v0
	v_max_f32_e32 v89, v1, v1
	v_max_f32_e32 v88, v88, v89
	v_max3_f32 v86, v86, v87, v88
	v_mov_b32_e32 v87, v86
	s_and_b64 vcc, exec, s[18:19]
	s_waitcnt lgkmcnt(0)
	s_nop 1
	v_permlane32_swap_b32_e32 v87, v86
	v_max_f32_e32 v86, v86, v87
	v_cmp_lt_f32_e64 s[44:45], s38, v86
	s_cbranch_vccnz .LBB0_675
	s_cmp_lg_u64 s[44:45], 0
	s_cselect_b64 s[20:21], -1, 0

.LBB0_690:
	v_cvt_f32_i32_e32 v4, v0
	s_cmp_eq_u32 s60, s52
	s_cselect_b64 s[44:45], -1, 0
	v_cndmask_b32_e64 v10, v169, 0, s[44:45]
	v_add_u32_e32 v14, s4, v166
	v_fma_f32 v4, -v154, v4, -v10
	ds_read_b128 v[10:13], v14
	s_mov_b32 s20, 2.0
	s_mov_b32 s22, 0x41200000
	s_mov_b32 s24, 0x41800000
	s_mov_b32 s28, 0x41900000
	s_mov_b32 s21, 0x40400000
	s_mov_b32 s23, 0x41300000
	s_mov_b32 s25, 0x41880000
	s_mov_b32 s29, 0x41980000
	v_fma_f32 v80, 0, v154, v4
	v_add_f32_e32 v81, v154, v4
	v_pk_fma_f32 v[82:83], v[154:155], s[20:21], v[4:5] op_sel_hi:[1,1,0]
	v_pk_fma_f32 v[84:85], v[154:155], s[38:39], v[4:5] op_sel_hi:[1,1,0]
	v_pk_fma_f32 v[86:87], v[154:155], s[22:23], v[4:5] op_sel_hi:[1,1,0]
	v_pk_fma_f32 v[88:89], v[154:155], s[24:25], v[4:5] op_sel_hi:[1,1,0]
	v_pk_fma_f32 v[90:91], v[154:155], s[28:29], v[4:5] op_sel_hi:[1,1,0]
	v_pk_fma_f32 v[92:93], v[154:155], s[26:27], v[4:5] op_sel_hi:[1,1,0]
	v_pk_fma_f32 v[94:95], v[154:155], s[36:37], v[4:5] op_sel_hi:[1,1,0]
	v_add_f32_e32 v4, v153, v4
	v_fma_f32 v96, 0, v154, v4
	s_waitcnt vmcnt(6) lgkmcnt(0)
	v_mfma_f32_32x32x16_bf16 v[80:95], v[10:13], v[112:115], v[80:95]
	ds_read_b128 v[10:13], v14 offset:32
	v_add_f32_e32 v97, v154, v4
	v_fma_f32 v98, v154, s20, v4
	v_fma_f32 v99, v155, s21, v4
	v_fma_f32 v100, v154, s38, v4
	v_fma_f32 v101, v155, s39, v4
	v_pk_fma_f32 v[102:103], v[154:155], s[22:23], v[4:5] op_sel_hi:[1,1,0]
	v_pk_fma_f32 v[104:105], v[154:155], s[24:25], v[4:5] op_sel_hi:[1,1,0]
	v_pk_fma_f32 v[106:107], v[154:155], s[28:29], v[4:5] op_sel_hi:[1,1,0]
	s_waitcnt vmcnt(5) lgkmcnt(0)
	v_mfma_f32_32x32x16_bf16 v[80:95], v[10:13], v[116:119], v[80:95]
	ds_read_b128 v[10:13], v14 offset:64
	v_fma_f32 v108, v154, s26, v4
	v_fma_f32 v109, v155, s27, v4
	v_fma_f32 v110, v154, s36, v4
	v_fma_f32 v111, v155, s37, v4
	s_cmp_lg_u32 s60, s52
	s_waitcnt vmcnt(4) lgkmcnt(0)
	v_mfma_f32_32x32x16_bf16 v[80:95], v[10:13], v[120:123], v[80:95]
	ds_read_b128 v[10:13], v14 offset:96
	ds_read_b128 v[170:173], v14 offset:4608
	s_waitcnt vmcnt(3) lgkmcnt(1)
	v_mfma_f32_32x32x16_bf16 v[80:95], v[10:13], v[124:127], v[80:95]
	ds_read_b128 v[10:13], v14 offset:4640
	s_waitcnt lgkmcnt(1)
	v_mfma_f32_32x32x16_bf16 v[96:111], v[170:173], v[112:115], v[96:111]
	s_nop 8
	v_max_f32_e32 v4, v81, v81
	s_waitcnt lgkmcnt(0)
	v_mfma_f32_32x32x16_bf16 v[96:111], v[10:13], v[116:119], v[96:111]
	ds_read_b128 v[10:13], v14 offset:4672
	s_waitcnt lgkmcnt(0)
	v_mfma_f32_32x32x16_bf16 v[96:111], v[10:13], v[120:123], v[96:111]
	ds_read_b128 v[10:13], v14 offset:4704
	s_waitcnt lgkmcnt(0)
	v_mfma_f32_32x32x16_bf16 v[96:111], v[10:13], v[124:127], v[96:111]
	s_nop 11
	v_max3_f32 v10, v97, v82, v98
	v_max3_f32 v4, v4, v83, v99
	v_max3_f32 v10, v10, v80, v96
	v_max3_f32 v4, v4, v84, v100
	v_max3_f32 v10, v10, v85, v101
	v_max3_f32 v4, v4, v86, v102
	v_max3_f32 v10, v10, v87, v103
	v_max3_f32 v4, v4, v88, v104
	v_max3_f32 v10, v10, v89, v105
	v_max3_f32 v4, v4, v90, v106
	v_max3_f32 v10, v10, v91, v107
	v_max3_f32 v4, v4, v92, v108
	v_max3_f32 v10, v10, v93, v109
	v_max3_f32 v4, v4, v94, v110
	v_max3_f32 v10, v10, v95, v111
	v_max_f32_e32 v4, v4, v10
	v_mov_b32_e32 v10, v4
	s_waitcnt lgkmcnt(0)
	s_nop 1
	v_permlane32_swap_b32_e32 v10, v4
	v_max_f32_e32 v4, v4, v10
	v_cmp_lt_f32_e32 vcc, s38, v4
	s_cbranch_scc0 .LBB0_695
	s_cmp_lg_u64 vcc, 0
	s_cselect_b64 s[20:21], -1, 0
	s_cbranch_execz .LBB0_696
	s_branch .LBB0_697

.LBB0_693:
	v_add_u32_e32 v4, 64, v0
	v_cvt_f32_i32_e32 v4, v4
	s_cmp_eq_u32 s5, s52
	s_cselect_b64 s[44:45], -1, 0
	v_cndmask_b32_e64 v7, v169, 0, s[44:45]
	v_fma_f32 v4, -v154, v4, -v7
	v_add_u32_e32 v7, s62, v166
	ds_read_b128 v[8:11], v7
	s_mov_b32 s20, 2.0
	s_mov_b32 s22, 0x41200000
	s_mov_b32 s24, 0x41800000
	s_mov_b32 s28, 0x41900000
	s_mov_b32 s21, 0x40400000
	s_mov_b32 s23, 0x41300000
	s_mov_b32 s25, 0x41880000
	s_mov_b32 s29, 0x41980000
	v_fma_f32 v80, 0, v154, v4
	v_add_f32_e32 v81, v154, v4
	v_pk_fma_f32 v[82:83], v[154:155], s[20:21], v[4:5] op_sel_hi:[1,1,0]
	v_pk_fma_f32 v[84:85], v[154:155], s[38:39], v[4:5] op_sel_hi:[1,1,0]
	v_pk_fma_f32 v[86:87], v[154:155], s[22:23], v[4:5] op_sel_hi:[1,1,0]
	v_pk_fma_f32 v[88:89], v[154:155], s[24:25], v[4:5] op_sel_hi:[1,1,0]
	v_pk_fma_f32 v[90:91], v[154:155], s[28:29], v[4:5] op_sel_hi:[1,1,0]
	v_pk_fma_f32 v[92:93], v[154:155], s[26:27], v[4:5] op_sel_hi:[1,1,0]
	v_pk_fma_f32 v[94:95], v[154:155], s[36:37], v[4:5] op_sel_hi:[1,1,0]
	v_add_f32_e32 v4, v153, v4
	v_fma_f32 v96, 0, v154, v4
	s_waitcnt vmcnt(6) lgkmcnt(0)
	v_mfma_f32_32x32x16_bf16 v[80:95], v[8:11], v[112:115], v[80:95]
	ds_read_b128 v[8:11], v7 offset:32
	v_add_f32_e32 v97, v154, v4
	v_fma_f32 v98, v154, s20, v4
	v_fma_f32 v99, v155, s21, v4
	v_fma_f32 v100, v154, s38, v4
	v_fma_f32 v101, v155, s39, v4
	v_pk_fma_f32 v[102:103], v[154:155], s[22:23], v[4:5] op_sel_hi:[1,1,0]
	v_pk_fma_f32 v[104:105], v[154:155], s[24:25], v[4:5] op_sel_hi:[1,1,0]
	v_pk_fma_f32 v[106:107], v[154:155], s[28:29], v[4:5] op_sel_hi:[1,1,0]
	s_waitcnt vmcnt(5) lgkmcnt(0)
	v_mfma_f32_32x32x16_bf16 v[80:95], v[8:11], v[116:119], v[80:95]
	ds_read_b128 v[8:11], v7 offset:64
	v_fma_f32 v108, v154, s26, v4
	v_fma_f32 v109, v155, s27, v4
	v_fma_f32 v110, v154, s36, v4
	v_fma_f32 v111, v155, s37, v4
	s_cmp_lg_u32 s5, s52
	s_waitcnt vmcnt(4) lgkmcnt(0)
	v_mfma_f32_32x32x16_bf16 v[80:95], v[8:11], v[120:123], v[80:95]
	ds_read_b128 v[8:11], v7 offset:96
	ds_read_b128 v[12:15], v7 offset:4608
	s_waitcnt vmcnt(3) lgkmcnt(1)
	v_mfma_f32_32x32x16_bf16 v[80:95], v[8:11], v[124:127], v[80:95]
	ds_read_b128 v[8:11], v7 offset:4640
	s_waitcnt lgkmcnt(1)
	v_mfma_f32_32x32x16_bf16 v[96:111], v[12:15], v[112:115], v[96:111]
	s_nop 8
	v_max_f32_e32 v4, v81, v81
	s_waitcnt lgkmcnt(0)
	v_mfma_f32_32x32x16_bf16 v[96:111], v[8:11], v[116:119], v[96:111]
	ds_read_b128 v[8:11], v7 offset:4672
	s_waitcnt lgkmcnt(0)
	v_mfma_f32_32x32x16_bf16 v[96:111], v[8:11], v[120:123], v[96:111]
	ds_read_b128 v[8:11], v7 offset:4704
	s_waitcnt lgkmcnt(0)
	v_mfma_f32_32x32x16_bf16 v[96:111], v[8:11], v[124:127], v[96:111]
	s_nop 11
	v_max3_f32 v7, v97, v82, v98
	v_max3_f32 v4, v4, v83, v99
	v_max3_f32 v7, v7, v80, v96
	v_max3_f32 v4, v4, v84, v100
	v_max3_f32 v7, v7, v85, v101
	v_max3_f32 v4, v4, v86, v102
	v_max3_f32 v7, v7, v87, v103
	v_max3_f32 v4, v4, v88, v104
	v_max3_f32 v7, v7, v89, v105
	v_max3_f32 v4, v4, v90, v106
	v_max3_f32 v7, v7, v91, v107
	v_max3_f32 v4, v4, v92, v108
	v_max3_f32 v7, v7, v93, v109
	v_max3_f32 v4, v4, v94, v110
	v_max3_f32 v7, v7, v95, v111
	v_max_f32_e32 v4, v4, v7
	v_mov_b32_e32 v7, v4
	s_waitcnt lgkmcnt(0)
	s_nop 1
	v_permlane32_swap_b32_e32 v7, v4
	v_max_f32_e32 v4, v4, v7
	v_cmp_lt_f32_e32 vcc, s38, v4
	s_cbranch_scc0 .LBB0_700
	s_cmp_lg_u64 vcc, 0
	s_cselect_b64 s[20:21], -1, 0
	s_cbranch_execz .LBB0_701
	s_branch .LBB0_702

.LBB0_720:
	v_cvt_f32_i32_e32 v4, v234
	s_cmp_eq_u32 s7, -1
	s_cselect_b64 s[16:17], -1, 0
	v_cndmask_b32_e64 v3, v225, 0, s[16:17]
	v_fma_f32 v4, -v154, v4, -v3
	s_mov_b32 s18, 2.0
	v_add_f32_e32 v6, v153, v4
	s_mov_b32 s19, 0x40400000
	v_pk_fma_f32 v[98:99], v[154:155], s[18:19], v[4:5] op_sel_hi:[1,1,0]
	v_pk_fma_f32 v[82:83], v[154:155], s[18:19], v[6:7] op_sel_hi:[1,1,0]
	s_mov_b32 s18, 0x41200000
	s_mov_b32 s19, 0x41300000
	v_pk_fma_f32 v[102:103], v[154:155], s[18:19], v[4:5] op_sel_hi:[1,1,0]
	v_pk_fma_f32 v[86:87], v[154:155], s[18:19], v[6:7] op_sel_hi:[1,1,0]
	s_mov_b32 s18, 0x41800000
	s_mov_b32 s19, 0x41880000
	v_pk_fma_f32 v[104:105], v[154:155], s[18:19], v[4:5] op_sel_hi:[1,1,0]
	v_pk_fma_f32 v[88:89], v[154:155], s[18:19], v[6:7] op_sel_hi:[1,1,0]
	s_mov_b32 s18, 0x41900000
	s_mov_b32 s19, 0x41980000
	v_fma_f32 v80, 0, v154, v6
	v_add_f32_e32 v81, v154, v6
	v_pk_fma_f32 v[84:85], v[154:155], s[38:39], v[6:7] op_sel_hi:[1,1,0]
	v_pk_fma_f32 v[90:91], v[154:155], s[18:19], v[6:7] op_sel_hi:[1,1,0]
	v_pk_fma_f32 v[92:93], v[154:155], s[26:27], v[6:7] op_sel_hi:[1,1,0]
	v_pk_fma_f32 v[94:95], v[154:155], s[36:37], v[6:7] op_sel_hi:[1,1,0]
	ds_read_b128 v[6:9], v222 offset:4608
	ds_read_b128 v[10:13], v222
	ds_read_b128 v[238:241], v222 offset:32
	v_fma_f32 v96, 0, v154, v4
	v_add_f32_e32 v97, v154, v4
	v_pk_fma_f32 v[100:101], v[154:155], s[38:39], v[4:5] op_sel_hi:[1,1,0]
	v_pk_fma_f32 v[106:107], v[154:155], s[18:19], v[4:5] op_sel_hi:[1,1,0]
	v_pk_fma_f32 v[108:109], v[154:155], s[26:27], v[4:5] op_sel_hi:[1,1,0]
	v_pk_fma_f32 v[110:111], v[154:155], s[36:37], v[4:5] op_sel_hi:[1,1,0]
	s_waitcnt lgkmcnt(2)
	v_mfma_f32_32x32x16_bf16 v[80:95], v[6:9], v[112:115], v[80:95]
	ds_read_b128 v[6:9], v222 offset:4640
	v_cmp_lt_i32_e32 vcc, 0, v234
	s_mov_b64 s[18:19], s[16:17]
	s_waitcnt lgkmcnt(2)
	v_mfma_f32_32x32x16_bf16 v[96:111], v[10:13], v[112:115], v[96:111]
	s_waitcnt lgkmcnt(1)
	v_mfma_f32_32x32x16_bf16 v[96:111], v[238:241], v[116:119], v[96:111]
	s_waitcnt lgkmcnt(0)
	v_mfma_f32_32x32x16_bf16 v[80:95], v[6:9], v[116:119], v[80:95]
	ds_read_b128 v[6:9], v222 offset:64
	ds_read_b128 v[10:13], v222 offset:4672
	s_waitcnt lgkmcnt(1)
	v_mfma_f32_32x32x16_bf16 v[96:111], v[6:9], v[120:123], v[96:111]
	s_waitcnt lgkmcnt(0)
	v_mfma_f32_32x32x16_bf16 v[80:95], v[10:13], v[120:123], v[80:95]
	ds_read_b128 v[6:9], v222 offset:96
	ds_read_b128 v[10:13], v222 offset:4704
	s_waitcnt lgkmcnt(1)
	v_mfma_f32_32x32x16_bf16 v[96:111], v[6:9], v[124:127], v[96:111]
	s_waitcnt lgkmcnt(0)
	v_mfma_f32_32x32x16_bf16 v[80:95], v[10:13], v[124:127], v[80:95]
	s_nop 9
	v_cndmask_b32_e32 v4, v196, v97, vcc
	v_cmp_lt_i32_e32 vcc, -1, v234
	s_nop 1
	v_cndmask_b32_e32 v243, v196, v96, vcc
	v_cmp_lt_i32_e32 vcc, 32, v234
	s_nop 1
	v_cndmask_b32_e32 v242, v196, v81, vcc
	v_cmp_lt_i32_e32 vcc, 31, v234
	s_nop 1
	v_cndmask_b32_e32 v244, v196, v80, vcc
	v_cmp_lt_i32_e32 vcc, 2, v234
	s_nop 1
	v_cndmask_b32_e32 v238, v196, v99, vcc
	v_cmp_lt_i32_e32 vcc, 1, v234
	s_nop 1
	v_cndmask_b32_e32 v240, v196, v98, vcc
	v_cmp_lt_i32_e32 vcc, 34, v234
	s_nop 1
	v_cndmask_b32_e32 v239, v196, v83, vcc
	v_cmp_lt_i32_e32 vcc, 33, v234
	s_nop 1
	v_cndmask_b32_e32 v241, v196, v82, vcc
	v_cmp_lt_i32_e32 vcc, 8, v234
	s_nop 1
	v_cndmask_b32_e32 v97, v196, v101, vcc
	v_cmp_lt_i32_e32 vcc, 7, v234
	s_nop 1
	v_cndmask_b32_e32 v99, v196, v100, vcc
	v_cmp_lt_i32_e32 vcc, 40, v234
	s_nop 1
	v_cndmask_b32_e32 v98, v196, v85, vcc
	v_cmp_lt_i32_e32 vcc, 39, v234
	s_nop 1
	v_cndmask_b32_e32 v100, v196, v84, vcc
	v_cmp_lt_i32_e32 vcc, 10, v234
	s_nop 1
	v_cndmask_b32_e32 v84, v196, v103, vcc
	v_cmp_lt_i32_e32 vcc, 9, v234
	s_nop 1
	v_cndmask_b32_e32 v96, v196, v102, vcc
	v_cmp_lt_i32_e32 vcc, 42, v234
	s_nop 1
	v_cndmask_b32_e32 v87, v196, v87, vcc
	v_cmp_lt_i32_e32 vcc, 41, v234
	s_nop 1
	v_cndmask_b32_e32 v86, v196, v86, vcc
	v_cmp_lt_i32_e32 vcc, 16, v234
	s_nop 1
	v_cndmask_b32_e32 v80, v196, v105, vcc
	v_cmp_lt_i32_e32 vcc, 15, v234
	s_nop 1
	v_cndmask_b32_e32 v83, v196, v104, vcc
	v_cmp_lt_i32_e32 vcc, 48, v234
	s_nop 1
	v_cndmask_b32_e32 v82, v196, v89, vcc
	v_cmp_lt_i32_e32 vcc, 47, v234
	v_max_f32_e32 v89, v242, v242
	s_nop 0
	v_cndmask_b32_e32 v85, v196, v88, vcc
	v_cmp_lt_i32_e32 vcc, 18, v234
	v_max_f32_e32 v88, v4, v4
	v_max_f32_e32 v88, v88, v89
	v_cndmask_b32_e32 v12, v196, v107, vcc
	v_cmp_lt_i32_e32 vcc, 17, v234
	v_max_f32_e32 v89, v240, v240
	v_max3_f32 v88, v243, v244, v88
	v_cndmask_b32_e32 v15, v196, v106, vcc
	v_cmp_lt_i32_e32 vcc, 50, v234
	s_nop 1
	v_cndmask_b32_e32 v14, v196, v91, vcc
	v_cmp_lt_i32_e32 vcc, 49, v234
	v_max_f32_e32 v91, v239, v239
	s_nop 0
	v_cndmask_b32_e32 v81, v196, v90, vcc
	v_max_f32_e32 v90, v241, v241
	v_max_f32_e32 v89, v89, v90
	v_max_f32_e32 v90, v238, v238
	v_max_f32_e32 v90, v90, v91
	v_max3_f32 v88, v88, v89, v90
	v_max_f32_e32 v89, v99, v99
	v_max_f32_e32 v90, v100, v100
	v_max_f32_e32 v89, v89, v90
	v_max_f32_e32 v90, v97, v97
	v_max_f32_e32 v91, v98, v98
	v_max_f32_e32 v90, v90, v91
	v_max3_f32 v88, v88, v89, v90
	v_max_f32_e32 v89, v96, v96
	v_max_f32_e32 v90, v86, v86
	v_max_f32_e32 v89, v89, v90
	v_max_f32_e32 v90, v84, v84
	v_max_f32_e32 v91, v87, v87
	v_max_f32_e32 v90, v90, v91
	v_cmp_lt_i32_e32 vcc, 24, v234
	v_max3_f32 v88, v88, v89, v90
	v_max_f32_e32 v89, v83, v83
	v_max_f32_e32 v90, v85, v85
	v_cndmask_b32_e32 v8, v196, v109, vcc
	v_cmp_lt_i32_e32 vcc, 23, v234
	v_max_f32_e32 v89, v89, v90
	v_max_f32_e32 v90, v80, v80
	v_max_f32_e32 v91, v82, v82
	v_cndmask_b32_e32 v11, v196, v108, vcc
	v_cmp_lt_i32_e32 vcc, 56, v234
	v_max_f32_e32 v90, v90, v91
	v_max3_f32 v88, v88, v89, v90
	v_cndmask_b32_e32 v10, v196, v93, vcc
	v_cmp_lt_i32_e32 vcc, 55, v234
	v_max_f32_e32 v89, v15, v15
	v_max_f32_e32 v90, v81, v81
	v_cndmask_b32_e32 v13, v196, v92, vcc
	v_cmp_lt_i32_e32 vcc, 26, v234
	v_max_f32_e32 v89, v89, v90
	v_max_f32_e32 v90, v12, v12
	v_max_f32_e32 v91, v14, v14
	v_cndmask_b32_e32 v3, v196, v111, vcc
	v_cmp_lt_i32_e32 vcc, 25, v234
	v_max_f32_e32 v90, v90, v91
	v_max3_f32 v88, v88, v89, v90
	v_cndmask_b32_e32 v7, v196, v110, vcc
	v_cmp_lt_i32_e32 vcc, 58, v234
	v_max_f32_e32 v89, v11, v11
	v_max_f32_e32 v90, v13, v13
	v_cndmask_b32_e32 v6, v196, v95, vcc
	v_cmp_lt_i32_e32 vcc, 57, v234
	v_max_f32_e32 v89, v89, v90
	v_max_f32_e32 v90, v8, v8
	v_max_f32_e32 v91, v10, v10
	v_cndmask_b32_e32 v9, v196, v94, vcc
	v_max_f32_e32 v90, v90, v91
	v_max3_f32 v88, v88, v89, v90
	v_max_f32_e32 v89, v7, v7
	v_max_f32_e32 v90, v9, v9
	v_max_f32_e32 v89, v89, v90
	v_max_f32_e32 v90, v3, v3
	v_max_f32_e32 v91, v6, v6
	v_max_f32_e32 v90, v90, v91
	v_max3_f32 v88, v88, v89, v90
	v_mov_b32_e32 v89, v88
	s_and_b64 vcc, exec, s[16:17]
	s_waitcnt lgkmcnt(0)
	s_nop 1
	v_permlane32_swap_b32_e32 v89, v88
	v_max_f32_e32 v88, v88, v89
	v_cmp_lt_f32_e64 s[44:45], s38, v88
	s_cbranch_vccnz .LBB0_722
	s_cmp_lg_u64 s[44:45], 0
	s_cselect_b64 s[18:19], -1, 0

.LBB0_726:
	v_add_u32_e32 v244, 64, v234
	v_cvt_f32_i32_e32 v1, v244
	s_cmp_eq_u32 s7, 0
	s_cselect_b64 s[16:17], -1, 0
	v_cndmask_b32_e64 v0, v225, 0, s[16:17]
	v_fma_f32 v0, -v154, v1, -v0
	s_mov_b32 s18, 2.0
	v_add_f32_e32 v2, v153, v0
	s_mov_b32 s19, 0x40400000
	v_pk_fma_f32 v[98:99], v[154:155], s[18:19], v[0:1] op_sel_hi:[1,1,0]
	v_pk_fma_f32 v[82:83], v[154:155], s[18:19], v[2:3] op_sel_hi:[1,1,0]
	s_mov_b32 s18, 0x41200000
	s_mov_b32 s19, 0x41300000
	v_pk_fma_f32 v[102:103], v[154:155], s[18:19], v[0:1] op_sel_hi:[1,1,0]
	v_pk_fma_f32 v[86:87], v[154:155], s[18:19], v[2:3] op_sel_hi:[1,1,0]
	s_mov_b32 s18, 0x41800000
	s_mov_b32 s19, 0x41880000
	v_pk_fma_f32 v[104:105], v[154:155], s[18:19], v[0:1] op_sel_hi:[1,1,0]
	v_pk_fma_f32 v[88:89], v[154:155], s[18:19], v[2:3] op_sel_hi:[1,1,0]
	s_mov_b32 s18, 0x41900000
	s_mov_b32 s19, 0x41980000
	v_fma_f32 v96, 0, v154, v0
	v_fma_f32 v80, 0, v154, v2
	v_add_f32_e32 v97, v154, v0
	v_add_f32_e32 v81, v154, v2
	v_pk_fma_f32 v[100:101], v[154:155], s[38:39], v[0:1] op_sel_hi:[1,1,0]
	v_pk_fma_f32 v[84:85], v[154:155], s[38:39], v[2:3] op_sel_hi:[1,1,0]
	v_pk_fma_f32 v[106:107], v[154:155], s[18:19], v[0:1] op_sel_hi:[1,1,0]
	v_pk_fma_f32 v[90:91], v[154:155], s[18:19], v[2:3] op_sel_hi:[1,1,0]
	v_pk_fma_f32 v[108:109], v[154:155], s[26:27], v[0:1] op_sel_hi:[1,1,0]
	v_pk_fma_f32 v[92:93], v[154:155], s[26:27], v[2:3] op_sel_hi:[1,1,0]
	v_pk_fma_f32 v[110:111], v[154:155], s[36:37], v[0:1] op_sel_hi:[1,1,0]
	v_pk_fma_f32 v[94:95], v[154:155], s[36:37], v[2:3] op_sel_hi:[1,1,0]
	ds_read_b128 v[0:3], v222 offset:13824
	ds_read_b128 v[6:9], v222 offset:9216
	ds_read_b128 v[10:13], v222 offset:9248
	s_waitcnt lgkmcnt(1)
	v_mfma_f32_32x32x16_bf16 v[96:111], v[6:9], v[112:115], v[96:111]
	v_cmp_lt_i32_e32 vcc, 0, v244
	s_mov_b64 s[18:19], s[16:17]
	v_mfma_f32_32x32x16_bf16 v[80:95], v[0:3], v[112:115], v[80:95]
	ds_read_b128 v[0:3], v222 offset:13856
	s_waitcnt lgkmcnt(1)
	v_mfma_f32_32x32x16_bf16 v[96:111], v[10:13], v[116:119], v[96:111]
	s_waitcnt lgkmcnt(0)
	v_mfma_f32_32x32x16_bf16 v[80:95], v[0:3], v[116:119], v[80:95]
	ds_read_b128 v[0:3], v222 offset:9280
	ds_read_b128 v[6:9], v222 offset:13888
	s_waitcnt lgkmcnt(1)
	v_mfma_f32_32x32x16_bf16 v[96:111], v[0:3], v[120:123], v[96:111]
	s_waitcnt lgkmcnt(0)
	v_mfma_f32_32x32x16_bf16 v[80:95], v[6:9], v[120:123], v[80:95]
	ds_read_b128 v[0:3], v222 offset:9312
	ds_read_b128 v[6:9], v222 offset:13920
	s_waitcnt lgkmcnt(1)
	v_mfma_f32_32x32x16_bf16 v[96:111], v[0:3], v[124:127], v[96:111]
	s_waitcnt lgkmcnt(0)
	v_mfma_f32_32x32x16_bf16 v[80:95], v[6:9], v[124:127], v[80:95]
	s_nop 9
	v_cndmask_b32_e32 v4, v196, v97, vcc
	v_cmp_lt_i32_e32 vcc, -1, v244
	s_nop 1
	v_cndmask_b32_e32 v242, v196, v96, vcc
	v_cmp_lt_i32_e32 vcc, 32, v244
	s_nop 1
	v_cndmask_b32_e32 v241, v196, v81, vcc
	v_cmp_lt_i32_e32 vcc, 31, v244
	s_nop 1
	v_cndmask_b32_e32 v243, v196, v80, vcc
	v_cmp_lt_i32_e32 vcc, 2, v244
	s_nop 1
	v_cndmask_b32_e32 v99, v196, v99, vcc
	v_cmp_lt_i32_e32 vcc, 1, v244
	s_nop 1
	v_cndmask_b32_e32 v239, v196, v98, vcc
	v_cmp_lt_i32_e32 vcc, 34, v244
	s_nop 1
	v_cndmask_b32_e32 v238, v196, v83, vcc
	v_cmp_lt_i32_e32 vcc, 33, v244
	s_nop 1
	v_cndmask_b32_e32 v240, v196, v82, vcc
	v_cmp_lt_i32_e32 vcc, 8, v244
	s_nop 1
	v_cndmask_b32_e32 v96, v196, v101, vcc
	v_cmp_lt_i32_e32 vcc, 7, v244
	s_nop 1
	v_cndmask_b32_e32 v98, v196, v100, vcc
	v_cmp_lt_i32_e32 vcc, 40, v244
	s_nop 1
	v_cndmask_b32_e32 v97, v196, v85, vcc
	v_cmp_lt_i32_e32 vcc, 39, v244
	s_nop 1
	v_cndmask_b32_e32 v100, v196, v84, vcc
	v_cmp_lt_i32_e32 vcc, 10, v244
	s_nop 1
	v_cndmask_b32_e32 v81, v196, v103, vcc
	v_cmp_lt_i32_e32 vcc, 9, v244
	s_nop 1
	v_cndmask_b32_e32 v84, v196, v102, vcc
	v_cmp_lt_i32_e32 vcc, 42, v244
	s_nop 1
	v_cndmask_b32_e32 v83, v196, v87, vcc
	v_cmp_lt_i32_e32 vcc, 41, v244
	v_max_f32_e32 v87, v241, v241
	s_nop 0
	v_cndmask_b32_e32 v85, v196, v86, vcc
	v_cmp_lt_i32_e32 vcc, 16, v244
	v_max_f32_e32 v86, v4, v4
	v_max_f32_e32 v86, v86, v87
	v_cndmask_b32_e32 v13, v196, v105, vcc
	v_cmp_lt_i32_e32 vcc, 15, v244
	v_max_f32_e32 v87, v239, v239
	v_max3_f32 v86, v242, v243, v86
	v_cndmask_b32_e32 v80, v196, v104, vcc
	v_cmp_lt_i32_e32 vcc, 48, v244
	s_nop 1
	v_cndmask_b32_e32 v15, v196, v89, vcc
	v_cmp_lt_i32_e32 vcc, 47, v244
	v_max_f32_e32 v89, v238, v238
	s_nop 0
	v_cndmask_b32_e32 v82, v196, v88, vcc
	v_max_f32_e32 v88, v240, v240
	v_max_f32_e32 v87, v87, v88
	v_max_f32_e32 v88, v99, v99
	v_max_f32_e32 v88, v88, v89
	v_max3_f32 v86, v86, v87, v88
	v_max_f32_e32 v87, v98, v98
	v_max_f32_e32 v88, v100, v100
	v_max_f32_e32 v87, v87, v88
	v_max_f32_e32 v88, v96, v96
	v_max_f32_e32 v89, v97, v97
	v_cmp_lt_i32_e32 vcc, 18, v244
	v_max_f32_e32 v88, v88, v89
	v_max3_f32 v86, v86, v87, v88
	v_cndmask_b32_e32 v9, v196, v107, vcc
	v_cmp_lt_i32_e32 vcc, 17, v244
	v_max_f32_e32 v87, v84, v84
	v_max_f32_e32 v88, v85, v85
	v_cndmask_b32_e32 v12, v196, v106, vcc
	v_cmp_lt_i32_e32 vcc, 50, v244
	v_max_f32_e32 v87, v87, v88
	v_max_f32_e32 v88, v81, v81
	v_max_f32_e32 v89, v83, v83
	v_cndmask_b32_e32 v11, v196, v91, vcc
	v_cmp_lt_i32_e32 vcc, 49, v244
	v_max_f32_e32 v88, v88, v89
	v_max3_f32 v86, v86, v87, v88
	v_cndmask_b32_e32 v14, v196, v90, vcc
	v_cmp_lt_i32_e32 vcc, 24, v244
	v_max_f32_e32 v87, v80, v80
	v_max_f32_e32 v88, v82, v82
	v_cndmask_b32_e32 v3, v196, v109, vcc
	v_cmp_lt_i32_e32 vcc, 23, v244
	v_max_f32_e32 v87, v87, v88
	v_max_f32_e32 v88, v13, v13
	v_max_f32_e32 v89, v15, v15
	v_cndmask_b32_e32 v8, v196, v108, vcc
	v_cmp_lt_i32_e32 vcc, 56, v244
	v_max_f32_e32 v88, v88, v89
	v_max3_f32 v86, v86, v87, v88
	v_cndmask_b32_e32 v7, v196, v93, vcc
	v_cmp_lt_i32_e32 vcc, 55, v244
	v_max_f32_e32 v87, v12, v12
	v_max_f32_e32 v88, v14, v14
	v_cndmask_b32_e32 v10, v196, v92, vcc
	v_cmp_lt_i32_e32 vcc, 26, v244
	v_max_f32_e32 v87, v87, v88
	v_max_f32_e32 v88, v9, v9
	v_max_f32_e32 v89, v11, v11
	v_cndmask_b32_e32 v0, v196, v111, vcc
	v_cmp_lt_i32_e32 vcc, 25, v244
	v_max_f32_e32 v88, v88, v89
	v_max3_f32 v86, v86, v87, v88
	v_cndmask_b32_e32 v2, v196, v110, vcc
	v_cmp_lt_i32_e32 vcc, 58, v244
	v_max_f32_e32 v87, v8, v8
	v_max_f32_e32 v88, v10, v10
	v_cndmask_b32_e32 v1, v196, v95, vcc
	v_cmp_lt_i32_e32 vcc, 57, v244
	v_max_f32_e32 v87, v87, v88
	v_max_f32_e32 v88, v3, v3
	v_max_f32_e32 v89, v7, v7
	v_cndmask_b32_e32 v6, v196, v94, vcc
	v_max_f32_e32 v88, v88, v89
	v_max3_f32 v86, v86, v87, v88
	v_max_f32_e32 v87, v2, v2
	v_max_f32_e32 v88, v6, v6
	v_max_f32_e32 v87, v87, v88
	v_max_f32_e32 v88, v0, v0
	v_max_f32_e32 v89, v1, v1
	v_max_f32_e32 v88, v88, v89
	v_max3_f32 v86, v86, v87, v88
	v_mov_b32_e32 v87, v86
	s_and_b64 vcc, exec, s[16:17]
	s_waitcnt lgkmcnt(0)
	s_nop 1
	v_permlane32_swap_b32_e32 v87, v86
	v_max_f32_e32 v86, v86, v87
	v_cmp_lt_f32_e64 s[44:45], s38, v86
	s_cbranch_vccnz .LBB0_728
	s_cmp_lg_u64 s[44:45], 0
	s_cselect_b64 s[18:19], -1, 0

.LBB0_743:
	v_cvt_f32_i32_e32 v4, v0
	s_cmp_eq_u32 s22, s7
	s_cselect_b64 s[44:45], -1, 0
	v_cndmask_b32_e64 v10, v225, 0, s[44:45]
	v_add_u32_e32 v14, s4, v222
	v_fma_f32 v4, -v154, v4, -v10
	ds_read_b128 v[10:13], v14
	s_mov_b32 s18, 2.0
	s_mov_b32 s20, 0x41200000
	s_mov_b32 s24, 0x41800000
	s_mov_b32 s28, 0x41900000
	s_mov_b32 s19, 0x40400000
	s_mov_b32 s21, 0x41300000
	s_mov_b32 s25, 0x41880000
	s_mov_b32 s29, 0x41980000
	v_fma_f32 v80, 0, v154, v4
	v_add_f32_e32 v81, v154, v4
	v_pk_fma_f32 v[82:83], v[154:155], s[18:19], v[4:5] op_sel_hi:[1,1,0]
	v_pk_fma_f32 v[84:85], v[154:155], s[38:39], v[4:5] op_sel_hi:[1,1,0]
	v_pk_fma_f32 v[86:87], v[154:155], s[20:21], v[4:5] op_sel_hi:[1,1,0]
	v_pk_fma_f32 v[88:89], v[154:155], s[24:25], v[4:5] op_sel_hi:[1,1,0]
	v_pk_fma_f32 v[90:91], v[154:155], s[28:29], v[4:5] op_sel_hi:[1,1,0]
	v_pk_fma_f32 v[92:93], v[154:155], s[26:27], v[4:5] op_sel_hi:[1,1,0]
	v_pk_fma_f32 v[94:95], v[154:155], s[36:37], v[4:5] op_sel_hi:[1,1,0]
	v_add_f32_e32 v4, v153, v4
	v_fma_f32 v96, 0, v154, v4
	s_waitcnt lgkmcnt(0)
	v_mfma_f32_32x32x16_bf16 v[80:95], v[10:13], v[112:115], v[80:95]
	ds_read_b128 v[10:13], v14 offset:32
	v_add_f32_e32 v97, v154, v4
	v_fma_f32 v98, v154, s18, v4
	v_fma_f32 v99, v155, s19, v4
	v_fma_f32 v100, v154, s38, v4
	v_fma_f32 v101, v155, s39, v4
	v_pk_fma_f32 v[102:103], v[154:155], s[20:21], v[4:5] op_sel_hi:[1,1,0]
	v_pk_fma_f32 v[104:105], v[154:155], s[24:25], v[4:5] op_sel_hi:[1,1,0]
	v_pk_fma_f32 v[106:107], v[154:155], s[28:29], v[4:5] op_sel_hi:[1,1,0]
	s_waitcnt lgkmcnt(0)
	v_mfma_f32_32x32x16_bf16 v[80:95], v[10:13], v[116:119], v[80:95]
	ds_read_b128 v[10:13], v14 offset:64
	v_fma_f32 v108, v154, s26, v4
	v_fma_f32 v109, v155, s27, v4
	v_fma_f32 v110, v154, s36, v4
	v_fma_f32 v111, v155, s37, v4
	s_cmp_lg_u32 s22, s7
	s_waitcnt lgkmcnt(0)
	v_mfma_f32_32x32x16_bf16 v[80:95], v[10:13], v[120:123], v[80:95]
	ds_read_b128 v[10:13], v14 offset:96
	ds_read_b128 v[226:229], v14 offset:4608
	s_waitcnt lgkmcnt(1)
	v_mfma_f32_32x32x16_bf16 v[80:95], v[10:13], v[124:127], v[80:95]
	ds_read_b128 v[10:13], v14 offset:4640
	s_waitcnt lgkmcnt(1)
	v_mfma_f32_32x32x16_bf16 v[96:111], v[226:229], v[112:115], v[96:111]
	s_nop 8
	v_max_f32_e32 v4, v81, v81
	s_waitcnt lgkmcnt(0)
	v_mfma_f32_32x32x16_bf16 v[96:111], v[10:13], v[116:119], v[96:111]
	ds_read_b128 v[10:13], v14 offset:4672
	s_waitcnt lgkmcnt(0)
	v_mfma_f32_32x32x16_bf16 v[96:111], v[10:13], v[120:123], v[96:111]
	ds_read_b128 v[10:13], v14 offset:4704
	s_waitcnt lgkmcnt(0)
	v_mfma_f32_32x32x16_bf16 v[96:111], v[10:13], v[124:127], v[96:111]
	s_nop 11
	v_max3_f32 v10, v97, v82, v98
	v_max3_f32 v4, v4, v83, v99
	v_max3_f32 v10, v10, v80, v96
	v_max3_f32 v4, v4, v84, v100
	v_max3_f32 v10, v10, v85, v101
	v_max3_f32 v4, v4, v86, v102
	v_max3_f32 v10, v10, v87, v103
	v_max3_f32 v4, v4, v88, v104
	v_max3_f32 v10, v10, v89, v105
	v_max3_f32 v4, v4, v90, v106
	v_max3_f32 v10, v10, v91, v107
	v_max3_f32 v4, v4, v92, v108
	v_max3_f32 v10, v10, v93, v109
	v_max3_f32 v4, v4, v94, v110
	v_max3_f32 v10, v10, v95, v111
	v_max_f32_e32 v4, v4, v10
	v_mov_b32_e32 v10, v4
	s_waitcnt lgkmcnt(0)
	s_nop 1
	v_permlane32_swap_b32_e32 v10, v4
	v_max_f32_e32 v4, v4, v10
	v_cmp_lt_f32_e32 vcc, s38, v4
	s_cbranch_scc0 .LBB0_748
	s_cmp_lg_u64 vcc, 0
	s_cselect_b64 s[18:19], -1, 0
	s_cbranch_execz .LBB0_749
	s_branch .LBB0_750

.LBB0_746:
	v_add_u32_e32 v4, 64, v0
	v_cvt_f32_i32_e32 v4, v4
	s_cmp_eq_u32 s48, s7
	s_cselect_b64 s[44:45], -1, 0
	v_cndmask_b32_e64 v7, v225, 0, s[44:45]
	v_fma_f32 v4, -v154, v4, -v7
	v_add_u32_e32 v7, s23, v222
	ds_read_b128 v[8:11], v7
	s_mov_b32 s18, 2.0
	s_mov_b32 s20, 0x41200000
	s_mov_b32 s24, 0x41800000
	s_mov_b32 s28, 0x41900000
	s_mov_b32 s19, 0x40400000
	s_mov_b32 s21, 0x41300000
	s_mov_b32 s25, 0x41880000
	s_mov_b32 s29, 0x41980000
	v_fma_f32 v80, 0, v154, v4
	v_add_f32_e32 v81, v154, v4
	v_pk_fma_f32 v[82:83], v[154:155], s[18:19], v[4:5] op_sel_hi:[1,1,0]
	v_pk_fma_f32 v[84:85], v[154:155], s[38:39], v[4:5] op_sel_hi:[1,1,0]
	v_pk_fma_f32 v[86:87], v[154:155], s[20:21], v[4:5] op_sel_hi:[1,1,0]
	v_pk_fma_f32 v[88:89], v[154:155], s[24:25], v[4:5] op_sel_hi:[1,1,0]
	v_pk_fma_f32 v[90:91], v[154:155], s[28:29], v[4:5] op_sel_hi:[1,1,0]
	v_pk_fma_f32 v[92:93], v[154:155], s[26:27], v[4:5] op_sel_hi:[1,1,0]
	v_pk_fma_f32 v[94:95], v[154:155], s[36:37], v[4:5] op_sel_hi:[1,1,0]
	v_add_f32_e32 v4, v153, v4
	v_fma_f32 v96, 0, v154, v4
	s_waitcnt lgkmcnt(0)
	v_mfma_f32_32x32x16_bf16 v[80:95], v[8:11], v[112:115], v[80:95]
	ds_read_b128 v[8:11], v7 offset:32
	v_add_f32_e32 v97, v154, v4
	v_fma_f32 v98, v154, s18, v4
	v_fma_f32 v99, v155, s19, v4
	v_fma_f32 v100, v154, s38, v4
	v_fma_f32 v101, v155, s39, v4
	v_pk_fma_f32 v[102:103], v[154:155], s[20:21], v[4:5] op_sel_hi:[1,1,0]
	v_pk_fma_f32 v[104:105], v[154:155], s[24:25], v[4:5] op_sel_hi:[1,1,0]
	v_pk_fma_f32 v[106:107], v[154:155], s[28:29], v[4:5] op_sel_hi:[1,1,0]
	s_waitcnt lgkmcnt(0)
	v_mfma_f32_32x32x16_bf16 v[80:95], v[8:11], v[116:119], v[80:95]
	ds_read_b128 v[8:11], v7 offset:64
	v_fma_f32 v108, v154, s26, v4
	v_fma_f32 v109, v155, s27, v4
	v_fma_f32 v110, v154, s36, v4
	v_fma_f32 v111, v155, s37, v4
	s_cmp_lg_u32 s48, s7
	s_waitcnt lgkmcnt(0)
	v_mfma_f32_32x32x16_bf16 v[80:95], v[8:11], v[120:123], v[80:95]
	ds_read_b128 v[8:11], v7 offset:96
	ds_read_b128 v[12:15], v7 offset:4608
	s_waitcnt lgkmcnt(1)
	v_mfma_f32_32x32x16_bf16 v[80:95], v[8:11], v[124:127], v[80:95]
	ds_read_b128 v[8:11], v7 offset:4640
	s_waitcnt lgkmcnt(1)
	v_mfma_f32_32x32x16_bf16 v[96:111], v[12:15], v[112:115], v[96:111]
	s_nop 8
	v_max_f32_e32 v4, v81, v81
	s_waitcnt lgkmcnt(0)
	v_mfma_f32_32x32x16_bf16 v[96:111], v[8:11], v[116:119], v[96:111]
	ds_read_b128 v[8:11], v7 offset:4672
	s_waitcnt lgkmcnt(0)
	v_mfma_f32_32x32x16_bf16 v[96:111], v[8:11], v[120:123], v[96:111]
	ds_read_b128 v[8:11], v7 offset:4704
	s_waitcnt lgkmcnt(0)
	v_mfma_f32_32x32x16_bf16 v[96:111], v[8:11], v[124:127], v[96:111]
	s_nop 11
	v_max3_f32 v7, v97, v82, v98
	v_max3_f32 v4, v4, v83, v99
	v_max3_f32 v7, v7, v80, v96
	v_max3_f32 v4, v4, v84, v100
	v_max3_f32 v7, v7, v85, v101
	v_max3_f32 v4, v4, v86, v102
	v_max3_f32 v7, v7, v87, v103
	v_max3_f32 v4, v4, v88, v104
	v_max3_f32 v7, v7, v89, v105
	v_max3_f32 v4, v4, v90, v106
	v_max3_f32 v7, v7, v91, v107
	v_max3_f32 v4, v4, v92, v108
	v_max3_f32 v7, v7, v93, v109
	v_max3_f32 v4, v4, v94, v110
	v_max3_f32 v7, v7, v95, v111
	v_max_f32_e32 v4, v4, v7
	v_mov_b32_e32 v7, v4
	s_waitcnt lgkmcnt(0)
	s_nop 1
	v_permlane32_swap_b32_e32 v7, v4
	v_max_f32_e32 v4, v4, v7
	v_cmp_lt_f32_e32 vcc, s38, v4
	s_cbranch_scc0 .LBB0_753
	s_cmp_lg_u64 vcc, 0
	s_cselect_b64 s[18:19], -1, 0
	s_cbranch_execz .LBB0_754
	s_branch .LBB0_755

.LBB0_1178:
	s_nop 4
	v_add_f32_e32 v159, v111, v1
	v_add_f32_e32 v1, v95, v227
	v_max3_f32 v4, v3, v161, v6
	v_max3_f32 v80, v164, v7, v165
	v_max3_f32 v4, v4, v160, v2
	v_max3_f32 v80, v80, v10, v168
	v_max3_f32 v4, v4, v11, v169
	v_max3_f32 v80, v80, v156, v172
	v_max3_f32 v4, v4, v157, v173
	v_max3_f32 v80, v80, v14, v170
	v_max3_f32 v4, v4, v15, v171
	v_max3_f32 v80, v80, v12, v166
	v_max3_f32 v4, v4, v13, v167
	v_max3_f32 v80, v80, v8, v162
	v_max3_f32 v4, v4, v9, v163
	v_max3_f32 v80, v80, v0, v158
	v_max3_f32 v4, v4, v159, v1
	v_max_f32_e32 v4, v4, v80
	v_mov_b32_e32 v80, v4
	s_andn2_b64 vcc, exec, s[18:19]
	s_waitcnt lgkmcnt(0)
	s_nop 1
	v_permlane32_swap_b32_e32 v80, v4
	v_max_f32_e32 v4, v4, v80
	v_cmp_lt_f32_e64 s[66:67], s38, v4
	s_cbranch_vccnz .LBB0_1180
	s_cmp_lg_u64 s[66:67], 0
	s_cselect_b64 s[20:21], -1, 0
